# code placement: every MFMA block of the four GEMM K-loops starts at an address 0 mod 8 (six s_nop pads in load segments)
# baseline (speedup 1.0000x reference)
; #define PG8_STAGE(bufoff, gbase, voff) do { _Pragma("unroll") for (int _i = 0; _i < 2; ++_i) \
;         __builtin_amdgcn_global_load_lds((const unsigned*)((const char*)(gbase) + (voff)[_i]), (PG8_LAS unsigned*)(lds + (bufoff) + ldsw + _i * 8192), 16, 0, 0); } while (0)
; #define PG8_LDA(dst, b, h) do { _Pragma("unroll") for (int m = 0; m < 4; ++m) _Pragma("unroll") for (int k = 0; k < 2; ++k) dst[m][k] = *(const PG8_LAS bf16x8*)(lds + PG8_SA(b, h) + aoff + m * 2048 + k * 1024); } while (0)
; #define PG8_LDB(dst, b, h) do { _Pragma("unroll") for (int n = 0; n < 2; ++n) _Pragma("unroll") for (int k = 0; k < 2; ++k) dst[n][k] = *(const PG8_LAS bf16x8*)(lds + PG8_SB(b, h) + boff + n * 2048 + k * 1024); } while (0)
; #define PG8_MMA(ai, bj, At, Bt) do { __builtin_amdgcn_s_setprio(1); _Pragma("unroll") for (int m = 0; m < 4; ++m) _Pragma("unroll") for (int n = 0; n < 2; ++n) _Pragma("unroll") for (int k = 0; k < 2; ++k) \
;         acc[ai][bj][m][n] = __builtin_amdgcn_mfma_f32_16x16x32_bf16(Bt[n][k], At[m][k], acc[ai][bj][m][n], 0, 0, 0); __builtin_amdgcn_s_setprio(0); } while (0)
; #define PG8_WAIT_V(n) asm volatile("s_waitcnt vmcnt(" #n ")" ::: "memory")
; #define PG8_WAIT_L(n) asm volatile("s_waitcnt lgkmcnt(" #n ")" ::: "memory")
; template <class Epi, class Sched, bool ALIGN_EPI = false, bool SP2 = false>
; __device__ __forceinline__ void gemm_phase(PG8_LAS unsigned char* lds, const Gemm g, const Sched& S, const Epi& E) {
;     ...
;             const bool last = (t == nt - 2);
;             const char* a1 = cA + (size_t)(t + 1) * kstep;
;             const char* a2 = last ? nA : cA + (size_t)(t + 2) * kstep; const char* b2 = last ? nB : cB + (size_t)(t + 2) * kstep;
;             const char* a3 = a2 + kstep; const char* b3 = b2 + kstep;
;             if (last && has_next) S.a_ready(nxt);
;             if constexpr (SP2) {
;             PG8_LDB(B0, 0, 0); PG8_LDB(B1, 0, 1); PG8_SCHED; PG8_LDA(At, 0, 0); PG8_STAGE(PG8_SA(1, 1), a1 + hstep, voffA);
;             PG8_WAIT_V(8); PG8_WAIT_L(0); PG8_BAR; PG8_MMA(0, 0, At, B0); PG8_MMA(0, 1, At, B1); PG8_BAR; PG8_SCHED;
;             PG8_LDA(At, 0, 1); PG8_STAGE(PG8_SB(0, 0), b2, voffB); PG8_STAGE(PG8_SB(0, 1), b2 + hstep, voffB); PG8_STAGE(PG8_SA(0, 0), a2, voffA);
;             PG8_WAIT_V(8); PG8_WAIT_L(0); PG8_BAR; PG8_MMA(1, 0, At, B0); PG8_MMA(1, 1, At, B1); PG8_BAR; PG8_SCHED;
.LBB0_132:
	s_add_u32 s18, s46, 0xfffc0080
	s_addc_u32 s38, s47, -1
	s_add_i32 s39, 0, 0x10000
	s_cmp_eq_u32 s85, 12
	s_cselect_b32 s81, s33, s38
	s_cselect_b32 s80, s73, s18
	v_add_u32_e32 v0, s39, v176
	s_cselect_b32 s45, s75, s84
	s_cselect_b32 s44, s82, s83
	s_add_i32 s18, 0, 0x14000
	ds_read_b128 v[144:147], v0
	ds_read_b128 v[148:151], v0 offset:1024
	ds_read_b128 v[152:155], v0 offset:2048
	ds_read_b128 v[156:159], v0 offset:3072
	v_add_u32_e32 v0, s18, v176
	ds_read_b128 v[160:163], v0
	ds_read_b128 v[164:167], v0 offset:1024
	ds_read_b128 v[168:171], v0 offset:2048
	ds_read_b128 v[172:175], v0 offset:3072
	v_lshl_add_u64 v[218:219], s[46:47], 0, v[140:141]
	s_add_i32 m0, s92, 0xc000
	ds_read_b128 v[180:183], v178
	ds_read_b128 v[184:187], v178 offset:1024
	ds_read_b128 v[188:191], v178 offset:2048
	ds_read_b128 v[192:195], v178 offset:3072
	ds_read_b128 v[202:205], v178 offset:4096
	ds_read_b128 v[206:209], v178 offset:5120
	ds_read_b128 v[210:213], v178 offset:6144
	ds_read_b128 v[214:217], v178 offset:7168
	global_load_lds_dwordx4 v[218:219], off
	v_lshl_add_u64 v[218:219], s[46:47], 0, v[142:143]
	s_add_i32 m0, s92, 0xe000
	s_nop 0
	global_load_lds_dwordx4 v[218:219], off
	s_waitcnt vmcnt(8)
	s_waitcnt lgkmcnt(0)
	s_barrier
	s_setprio 1
	v_mfma_f32_16x16x32_bf16 v[118:121], v[144:147], v[180:183], v[118:121]
	v_mfma_f32_16x16x32_bf16 v[118:121], v[148:151], v[184:187], v[118:121]
	v_mfma_f32_16x16x32_bf16 v[102:105], v[144:147], v[188:191], v[102:105]
	v_mfma_f32_16x16x32_bf16 v[102:105], v[148:151], v[192:195], v[102:105]
	v_mfma_f32_16x16x32_bf16 v[86:89], v[144:147], v[202:205], v[86:89]
	v_mfma_f32_16x16x32_bf16 v[86:89], v[148:151], v[206:209], v[86:89]
	v_mfma_f32_16x16x32_bf16 v[70:73], v[144:147], v[210:213], v[70:73]
	v_mfma_f32_16x16x32_bf16 v[70:73], v[148:151], v[214:217], v[70:73]
	v_mfma_f32_16x16x32_bf16 v[114:117], v[152:155], v[180:183], v[114:117]
	v_mfma_f32_16x16x32_bf16 v[114:117], v[156:159], v[184:187], v[114:117]
	v_mfma_f32_16x16x32_bf16 v[98:101], v[152:155], v[188:191], v[98:101]
	v_mfma_f32_16x16x32_bf16 v[98:101], v[156:159], v[192:195], v[98:101]
	v_mfma_f32_16x16x32_bf16 v[82:85], v[152:155], v[202:205], v[82:85]
	v_mfma_f32_16x16x32_bf16 v[82:85], v[156:159], v[206:209], v[82:85]
	v_mfma_f32_16x16x32_bf16 v[66:69], v[152:155], v[210:213], v[66:69]
	v_mfma_f32_16x16x32_bf16 v[66:69], v[156:159], v[214:217], v[66:69]
	v_mfma_f32_16x16x32_bf16 v[126:129], v[160:163], v[180:183], v[126:129]
	v_mfma_f32_16x16x32_bf16 v[126:129], v[164:167], v[184:187], v[126:129]
	v_mfma_f32_16x16x32_bf16 v[110:113], v[160:163], v[188:191], v[110:113]
	v_mfma_f32_16x16x32_bf16 v[110:113], v[164:167], v[192:195], v[110:113]
	v_mfma_f32_16x16x32_bf16 v[94:97], v[160:163], v[202:205], v[94:97]
	v_mfma_f32_16x16x32_bf16 v[94:97], v[164:167], v[206:209], v[94:97]
	v_mfma_f32_16x16x32_bf16 v[78:81], v[160:163], v[210:213], v[78:81]
	v_mfma_f32_16x16x32_bf16 v[78:81], v[164:167], v[214:217], v[78:81]
	v_mfma_f32_16x16x32_bf16 v[122:125], v[168:171], v[180:183], v[122:125]
	v_mfma_f32_16x16x32_bf16 v[122:125], v[172:175], v[184:187], v[122:125]
	v_mfma_f32_16x16x32_bf16 v[106:109], v[168:171], v[188:191], v[106:109]
	v_mfma_f32_16x16x32_bf16 v[106:109], v[172:175], v[192:195], v[106:109]
	v_mfma_f32_16x16x32_bf16 v[90:93], v[168:171], v[202:205], v[90:93]
	v_mfma_f32_16x16x32_bf16 v[90:93], v[172:175], v[206:209], v[90:93]
	v_mfma_f32_16x16x32_bf16 v[74:77], v[168:171], v[210:213], v[74:77]
	v_mfma_f32_16x16x32_bf16 v[74:77], v[172:175], v[214:217], v[74:77]
	s_setprio 0
	s_barrier
	s_add_i32 s38, s39, s91
	v_lshl_add_u64 v[218:219], s[44:45], 0, v[134:135]
	s_mov_b32 m0, s38
	ds_read_b128 v[180:183], v178 offset:16384
	ds_read_b128 v[184:187], v178 offset:17408
	ds_read_b128 v[188:191], v178 offset:18432
	ds_read_b128 v[192:195], v178 offset:19456
	ds_read_b128 v[202:205], v178 offset:20480
	ds_read_b128 v[206:209], v178 offset:21504
	ds_read_b128 v[210:213], v178 offset:22528
	ds_read_b128 v[214:217], v178 offset:23552
	global_load_lds_dwordx4 v[218:219], off
	s_add_i32 m0, s38, 0x2000
	s_add_u32 s38, s44, 0x40000
	v_lshl_add_u64 v[220:221], s[44:45], 0, v[130:131]
	s_addc_u32 s39, s45, 0
	s_add_i32 s18, s18, s91
	global_load_lds_dwordx4 v[220:221], off
	v_lshl_add_u64 v[222:223], s[38:39], 0, v[134:135]
	s_mov_b32 m0, s18
	v_lshl_add_u64 v[224:225], s[80:81], 0, v[132:133]
	global_load_lds_dwordx4 v[222:223], off
	v_lshl_add_u64 v[222:223], s[38:39], 0, v[130:131]
	s_add_i32 m0, s18, 0x2000
	s_nop 0
	global_load_lds_dwordx4 v[222:223], off
	v_lshl_add_u64 v[222:223], s[80:81], 0, v[136:137]
	s_mov_b32 m0, s92
	s_nop 0
	global_load_lds_dwordx4 v[222:223], off
	s_mov_b32 m0, s93
	s_nop 0
	global_load_lds_dwordx4 v[224:225], off
	s_waitcnt vmcnt(8)
	s_waitcnt lgkmcnt(0)
	s_barrier
; #define PG8_STAGE(bufoff, gbase, voff) do { _Pragma("unroll") for (int _i = 0; _i < 2; ++_i) \
;         __builtin_amdgcn_global_load_lds((const unsigned*)((const char*)(gbase) + (voff)[_i]), (PG8_LAS unsigned*)(lds + (bufoff) + ldsw + _i * 8192), 16, 0, 0); } while (0)
; #define PG8_LDA(dst, b, h) do { _Pragma("unroll") for (int m = 0; m < 4; ++m) _Pragma("unroll") for (int k = 0; k < 2; ++k) dst[m][k] = *(const PG8_LAS bf16x8*)(lds + PG8_SA(b, h) + aoff + m * 2048 + k * 1024); } while (0)
; #define PG8_LDB(dst, b, h) do { _Pragma("unroll") for (int n = 0; n < 2; ++n) _Pragma("unroll") for (int k = 0; k < 2; ++k) dst[n][k] = *(const PG8_LAS bf16x8*)(lds + PG8_SB(b, h) + boff + n * 2048 + k * 1024); } while (0)
; #define PG8_MMA(ai, bj, At, Bt) do { __builtin_amdgcn_s_setprio(1); _Pragma("unroll") for (int m = 0; m < 4; ++m) _Pragma("unroll") for (int n = 0; n < 2; ++n) _Pragma("unroll") for (int k = 0; k < 2; ++k) \
;         acc[ai][bj][m][n] = __builtin_amdgcn_mfma_f32_16x16x32_bf16(Bt[n][k], At[m][k], acc[ai][bj][m][n], 0, 0, 0); __builtin_amdgcn_s_setprio(0); } while (0)
; #define PG8_WAIT_V(n) asm volatile("s_waitcnt vmcnt(" #n ")" ::: "memory")
; #define PG8_WAIT_L(n) asm volatile("s_waitcnt lgkmcnt(" #n ")" ::: "memory")
; #define PG8_BAR __builtin_amdgcn_s_barrier()
; #define PG8_SCHED __builtin_amdgcn_sched_barrier(0)
; template <class Epi, class Sched, bool ALIGN_EPI = false, bool SP2 = false>
; __device__ __forceinline__ void gemm_phase(PG8_LAS unsigned char* lds, const Gemm g, const Sched& S, const Epi& E) {
;     ...
;             PG8_WAIT_V(8); PG8_WAIT_L(0); PG8_BAR; PG8_MMA(1, 0, At, B0); PG8_MMA(1, 1, At, B1); PG8_BAR; PG8_SCHED;
;             PG8_LDB(B0, 1, 0); PG8_LDB(B1, 1, 1); PG8_SCHED; PG8_LDA(At, 1, 0); PG8_STAGE(PG8_SA(0, 1), a2 + hstep, voffA);
;             PG8_WAIT_V(8); PG8_WAIT_L(0); PG8_BAR; PG8_MMA(0, 0, At, B0); PG8_MMA(0, 1, At, B1); PG8_BAR; PG8_SCHED;
	s_setprio 1
	v_mfma_f32_16x16x32_bf16 v[54:57], v[144:147], v[180:183], v[54:57]
	v_mfma_f32_16x16x32_bf16 v[54:57], v[148:151], v[184:187], v[54:57]
	v_mfma_f32_16x16x32_bf16 v[38:41], v[144:147], v[188:191], v[38:41]
	v_mfma_f32_16x16x32_bf16 v[38:41], v[148:151], v[192:195], v[38:41]
	v_mfma_f32_16x16x32_bf16 v[22:25], v[144:147], v[202:205], v[22:25]
	v_mfma_f32_16x16x32_bf16 v[22:25], v[148:151], v[206:209], v[22:25]
	v_mfma_f32_16x16x32_bf16 v[6:9], v[144:147], v[210:213], v[6:9]
	v_mfma_f32_16x16x32_bf16 v[6:9], v[148:151], v[214:217], v[6:9]
	v_mfma_f32_16x16x32_bf16 v[50:53], v[152:155], v[180:183], v[50:53]
	v_mfma_f32_16x16x32_bf16 v[50:53], v[156:159], v[184:187], v[50:53]
	v_mfma_f32_16x16x32_bf16 v[34:37], v[152:155], v[188:191], v[34:37]
	v_mfma_f32_16x16x32_bf16 v[34:37], v[156:159], v[192:195], v[34:37]
	v_mfma_f32_16x16x32_bf16 v[18:21], v[152:155], v[202:205], v[18:21]
	v_mfma_f32_16x16x32_bf16 v[18:21], v[156:159], v[206:209], v[18:21]
	v_mfma_f32_16x16x32_bf16 v[2:5], v[152:155], v[210:213], v[2:5]
	v_mfma_f32_16x16x32_bf16 v[2:5], v[156:159], v[214:217], v[2:5]
	v_mfma_f32_16x16x32_bf16 v[62:65], v[160:163], v[180:183], v[62:65]
	v_mfma_f32_16x16x32_bf16 v[62:65], v[164:167], v[184:187], v[62:65]
	v_mfma_f32_16x16x32_bf16 v[46:49], v[160:163], v[188:191], v[46:49]
	v_mfma_f32_16x16x32_bf16 v[46:49], v[164:167], v[192:195], v[46:49]
	v_mfma_f32_16x16x32_bf16 v[30:33], v[160:163], v[202:205], v[30:33]
	v_mfma_f32_16x16x32_bf16 v[30:33], v[164:167], v[206:209], v[30:33]
	v_mfma_f32_16x16x32_bf16 v[10:13], v[160:163], v[210:213], v[10:13]
	v_mfma_f32_16x16x32_bf16 v[10:13], v[164:167], v[214:217], v[10:13]
	v_mfma_f32_16x16x32_bf16 v[58:61], v[168:171], v[180:183], v[58:61]
	v_mfma_f32_16x16x32_bf16 v[58:61], v[172:175], v[184:187], v[58:61]
	v_mfma_f32_16x16x32_bf16 v[42:45], v[168:171], v[188:191], v[42:45]
	v_mfma_f32_16x16x32_bf16 v[42:45], v[172:175], v[192:195], v[42:45]
	v_mfma_f32_16x16x32_bf16 v[26:29], v[168:171], v[202:205], v[26:29]
	v_mfma_f32_16x16x32_bf16 v[26:29], v[172:175], v[206:209], v[26:29]
	v_mfma_f32_16x16x32_bf16 v[14:17], v[168:171], v[210:213], v[14:17]
	v_mfma_f32_16x16x32_bf16 v[14:17], v[172:175], v[214:217], v[14:17]
	s_setprio 0
	s_barrier
	s_add_i32 s18, 0, 0x18000
	v_add_u32_e32 v0, s18, v176
	s_add_i32 vcc_lo, 0, 0x1c000
	ds_read_b128 v[144:147], v0
	ds_read_b128 v[148:151], v0 offset:1024
	ds_read_b128 v[152:155], v0 offset:2048
	ds_read_b128 v[156:159], v0 offset:3072
	v_add_u32_e32 v0, vcc_lo, v176
	ds_read_b128 v[160:163], v0
	ds_read_b128 v[164:167], v0 offset:1024
	ds_read_b128 v[168:171], v0 offset:2048
	ds_read_b128 v[172:175], v0 offset:3072
	s_add_u32 s38, s80, 0x40000
	s_addc_u32 s39, s81, 0
	s_mov_b32 m0, s94
	v_lshl_add_u64 v[226:227], s[38:39], 0, v[136:137]
	ds_read_b128 v[180:183], v178 offset:32768
	ds_read_b128 v[184:187], v178 offset:33792
	ds_read_b128 v[188:191], v178 offset:34816
	ds_read_b128 v[192:195], v178 offset:35840
	ds_read_b128 v[202:205], v178 offset:36864
	ds_read_b128 v[206:209], v178 offset:37888
	ds_read_b128 v[210:213], v178 offset:38912
	ds_read_b128 v[214:217], v178 offset:39936
	global_load_lds_dwordx4 v[226:227], off
	v_lshl_add_u64 v[226:227], s[38:39], 0, v[132:133]
	s_mov_b32 m0, s95
	s_nop 0
	global_load_lds_dwordx4 v[226:227], off
	s_waitcnt vmcnt(8)
	s_waitcnt lgkmcnt(0)
	s_barrier
	s_setprio 1
	v_mfma_f32_16x16x32_bf16 v[118:121], v[144:147], v[180:183], v[118:121]
	v_mfma_f32_16x16x32_bf16 v[118:121], v[148:151], v[184:187], v[118:121]
	v_mfma_f32_16x16x32_bf16 v[102:105], v[144:147], v[188:191], v[102:105]
	v_mfma_f32_16x16x32_bf16 v[102:105], v[148:151], v[192:195], v[102:105]
	v_mfma_f32_16x16x32_bf16 v[86:89], v[144:147], v[202:205], v[86:89]
	v_mfma_f32_16x16x32_bf16 v[86:89], v[148:151], v[206:209], v[86:89]
	v_mfma_f32_16x16x32_bf16 v[70:73], v[144:147], v[210:213], v[70:73]
	v_mfma_f32_16x16x32_bf16 v[70:73], v[148:151], v[214:217], v[70:73]
	v_mfma_f32_16x16x32_bf16 v[114:117], v[152:155], v[180:183], v[114:117]
	v_mfma_f32_16x16x32_bf16 v[114:117], v[156:159], v[184:187], v[114:117]
	v_mfma_f32_16x16x32_bf16 v[98:101], v[152:155], v[188:191], v[98:101]
	v_mfma_f32_16x16x32_bf16 v[98:101], v[156:159], v[192:195], v[98:101]
	v_mfma_f32_16x16x32_bf16 v[82:85], v[152:155], v[202:205], v[82:85]
	v_mfma_f32_16x16x32_bf16 v[82:85], v[156:159], v[206:209], v[82:85]
	v_mfma_f32_16x16x32_bf16 v[66:69], v[152:155], v[210:213], v[66:69]
	v_mfma_f32_16x16x32_bf16 v[66:69], v[156:159], v[214:217], v[66:69]
	v_mfma_f32_16x16x32_bf16 v[126:129], v[160:163], v[180:183], v[126:129]
	v_mfma_f32_16x16x32_bf16 v[126:129], v[164:167], v[184:187], v[126:129]
	v_mfma_f32_16x16x32_bf16 v[110:113], v[160:163], v[188:191], v[110:113]
	v_mfma_f32_16x16x32_bf16 v[110:113], v[164:167], v[192:195], v[110:113]
	v_mfma_f32_16x16x32_bf16 v[94:97], v[160:163], v[202:205], v[94:97]
	v_mfma_f32_16x16x32_bf16 v[94:97], v[164:167], v[206:209], v[94:97]
	v_mfma_f32_16x16x32_bf16 v[78:81], v[160:163], v[210:213], v[78:81]
	v_mfma_f32_16x16x32_bf16 v[78:81], v[164:167], v[214:217], v[78:81]
	v_mfma_f32_16x16x32_bf16 v[122:125], v[168:171], v[180:183], v[122:125]
	v_mfma_f32_16x16x32_bf16 v[122:125], v[172:175], v[184:187], v[122:125]
	v_mfma_f32_16x16x32_bf16 v[106:109], v[168:171], v[188:191], v[106:109]
	v_mfma_f32_16x16x32_bf16 v[106:109], v[172:175], v[192:195], v[106:109]
	v_mfma_f32_16x16x32_bf16 v[90:93], v[168:171], v[202:205], v[90:93]
	v_mfma_f32_16x16x32_bf16 v[90:93], v[172:175], v[206:209], v[90:93]
	v_mfma_f32_16x16x32_bf16 v[74:77], v[168:171], v[210:213], v[74:77]
	v_mfma_f32_16x16x32_bf16 v[74:77], v[172:175], v[214:217], v[74:77]
	s_setprio 0
	s_barrier
; #define PG8_STAGE(bufoff, gbase, voff) do { _Pragma("unroll") for (int _i = 0; _i < 2; ++_i) \
;         __builtin_amdgcn_global_load_lds((const unsigned*)((const char*)(gbase) + (voff)[_i]), (PG8_LAS unsigned*)(lds + (bufoff) + ldsw + _i * 8192), 16, 0, 0); } while (0)
; #define PG8_LDA(dst, b, h) do { _Pragma("unroll") for (int m = 0; m < 4; ++m) _Pragma("unroll") for (int k = 0; k < 2; ++k) dst[m][k] = *(const PG8_LAS bf16x8*)(lds + PG8_SA(b, h) + aoff + m * 2048 + k * 1024); } while (0)
; #define PG8_MMA(ai, bj, At, Bt) do { __builtin_amdgcn_s_setprio(1); _Pragma("unroll") for (int m = 0; m < 4; ++m) _Pragma("unroll") for (int n = 0; n < 2; ++n) _Pragma("unroll") for (int k = 0; k < 2; ++k) \
;         acc[ai][bj][m][n] = __builtin_amdgcn_mfma_f32_16x16x32_bf16(Bt[n][k], At[m][k], acc[ai][bj][m][n], 0, 0, 0); __builtin_amdgcn_s_setprio(0); } while (0)
; #define PG8_WAIT_V(n) asm volatile("s_waitcnt vmcnt(" #n ")" ::: "memory")
; #define PG8_WAIT_L(n) asm volatile("s_waitcnt lgkmcnt(" #n ")" ::: "memory")
; #define PG8_BAR __builtin_amdgcn_s_barrier()
; #define PG8_SCHED __builtin_amdgcn_sched_barrier(0)
; template <class Epi, class Sched, bool ALIGN_EPI = false, bool SP2 = false>
; __device__ __forceinline__ void gemm_phase(PG8_LAS unsigned char* lds, const Gemm g, const Sched& S, const Epi& E) {
;     ...
;             PG8_LDA(At, 1, 1); PG8_STAGE(PG8_SB(1, 0), b3, voffB); PG8_STAGE(PG8_SB(1, 1), b3 + hstep, voffB); PG8_STAGE(PG8_SA(1, 0), a3, voffA);
;             PG8_WAIT_V(8); PG8_WAIT_L(0); PG8_BAR; PG8_MMA(1, 0, At, B0); PG8_MMA(1, 1, At, B1); PG8_BAR; PG8_SCHED;
;     ...
;         if constexpr (ALIGN_EPI) { if (wr == 0) PG8_BAR; }
	s_add_i32 s18, s18, s91
	v_lshl_add_u64 v[218:219], v[218:219], 0, s[30:31]
	s_mov_b32 m0, s18
	ds_read_b128 v[180:183], v178 offset:49152
	ds_read_b128 v[184:187], v178 offset:50176
	ds_read_b128 v[188:191], v178 offset:51200
	ds_read_b128 v[192:195], v178 offset:52224
	ds_read_b128 v[202:205], v178 offset:53248
	ds_read_b128 v[206:209], v178 offset:54272
	ds_read_b128 v[210:213], v178 offset:55296
	ds_read_b128 v[214:217], v178 offset:56320
	global_load_lds_dwordx4 v[218:219], off
	s_add_i32 m0, s18, 0x2000
	s_add_u32 s38, s44, 0x40080
	v_lshl_add_u64 v[218:219], v[220:221], 0, s[30:31]
	s_addc_u32 s39, s45, 0
	s_add_i32 s18, vcc_lo, s91
	global_load_lds_dwordx4 v[218:219], off
	v_lshl_add_u64 v[218:219], s[38:39], 0, v[134:135]
	s_mov_b32 m0, s18
	s_nop 0
	global_load_lds_dwordx4 v[218:219], off
	v_lshl_add_u64 v[218:219], s[38:39], 0, v[130:131]
	s_add_i32 m0, s18, 0x2000
	s_nop 0
	global_load_lds_dwordx4 v[218:219], off
	v_lshl_add_u64 v[218:219], v[222:223], 0, s[30:31]
	s_mov_b32 m0, s7
	s_nop 0
	global_load_lds_dwordx4 v[218:219], off
	v_lshl_add_u64 v[218:219], v[224:225], 0, s[30:31]
	s_mov_b32 m0, s96
	s_nop 0
	global_load_lds_dwordx4 v[218:219], off
	s_nop 0
	s_waitcnt vmcnt(8)
	s_waitcnt lgkmcnt(0)
	s_barrier
	s_setprio 1
	v_mfma_f32_16x16x32_bf16 v[54:57], v[144:147], v[180:183], v[54:57]
	v_mfma_f32_16x16x32_bf16 v[54:57], v[148:151], v[184:187], v[54:57]
	v_mfma_f32_16x16x32_bf16 v[38:41], v[144:147], v[188:191], v[38:41]
	v_mfma_f32_16x16x32_bf16 v[38:41], v[148:151], v[192:195], v[38:41]
	v_mfma_f32_16x16x32_bf16 v[22:25], v[144:147], v[202:205], v[22:25]
	v_mfma_f32_16x16x32_bf16 v[22:25], v[148:151], v[206:209], v[22:25]
	v_mfma_f32_16x16x32_bf16 v[6:9], v[144:147], v[210:213], v[6:9]
	v_mfma_f32_16x16x32_bf16 v[6:9], v[148:151], v[214:217], v[6:9]
	v_mfma_f32_16x16x32_bf16 v[50:53], v[152:155], v[180:183], v[50:53]
	v_mfma_f32_16x16x32_bf16 v[50:53], v[156:159], v[184:187], v[50:53]
	v_mfma_f32_16x16x32_bf16 v[34:37], v[152:155], v[188:191], v[34:37]
	v_mfma_f32_16x16x32_bf16 v[34:37], v[156:159], v[192:195], v[34:37]
	v_mfma_f32_16x16x32_bf16 v[18:21], v[152:155], v[202:205], v[18:21]
	v_mfma_f32_16x16x32_bf16 v[18:21], v[156:159], v[206:209], v[18:21]
	v_mfma_f32_16x16x32_bf16 v[2:5], v[152:155], v[210:213], v[2:5]
	v_mfma_f32_16x16x32_bf16 v[2:5], v[156:159], v[214:217], v[2:5]
	v_mfma_f32_16x16x32_bf16 v[62:65], v[160:163], v[180:183], v[62:65]
	v_mfma_f32_16x16x32_bf16 v[62:65], v[164:167], v[184:187], v[62:65]
	v_mfma_f32_16x16x32_bf16 v[46:49], v[160:163], v[188:191], v[46:49]
	v_mfma_f32_16x16x32_bf16 v[46:49], v[164:167], v[192:195], v[46:49]
	v_mfma_f32_16x16x32_bf16 v[30:33], v[160:163], v[202:205], v[30:33]
	v_mfma_f32_16x16x32_bf16 v[30:33], v[164:167], v[206:209], v[30:33]
	v_mfma_f32_16x16x32_bf16 v[10:13], v[160:163], v[210:213], v[10:13]
	v_mfma_f32_16x16x32_bf16 v[10:13], v[164:167], v[214:217], v[10:13]
	v_mfma_f32_16x16x32_bf16 v[58:61], v[168:171], v[180:183], v[58:61]
	v_mfma_f32_16x16x32_bf16 v[58:61], v[172:175], v[184:187], v[58:61]
	v_mfma_f32_16x16x32_bf16 v[42:45], v[168:171], v[188:191], v[42:45]
	v_mfma_f32_16x16x32_bf16 v[42:45], v[172:175], v[192:195], v[42:45]
	v_mfma_f32_16x16x32_bf16 v[26:29], v[168:171], v[202:205], v[26:29]
	v_mfma_f32_16x16x32_bf16 v[26:29], v[172:175], v[206:209], v[26:29]
	v_mfma_f32_16x16x32_bf16 v[14:17], v[168:171], v[210:213], v[14:17]
	v_mfma_f32_16x16x32_bf16 v[14:17], v[172:175], v[214:217], v[14:17]
	s_setprio 0
	s_barrier
	s_add_i32 s85, s85, 2
	s_add_u32 s46, s46, 0x100
	s_addc_u32 s47, s47, 0
	s_add_u32 s83, s83, 0x100
	s_addc_u32 s84, s84, 0
	s_cmp_gt_u32 s85, 13
	s_cbranch_scc0 .LBB0_132
	s_and_b64 vcc, exec, s[10:11]
	s_cbranch_vccz .LBB0_135
	s_barrier

; #define PG8_STAGE(bufoff, gbase, voff) do { _Pragma("unroll") for (int _i = 0; _i < 2; ++_i) \
;         __builtin_amdgcn_global_load_lds((const unsigned*)((const char*)(gbase) + (voff)[_i]), (PG8_LAS unsigned*)(lds + (bufoff) + ldsw + _i * 8192), 16, 0, 0); } while (0)
; #define PG8_LDA(dst, b, h) do { _Pragma("unroll") for (int m = 0; m < 4; ++m) _Pragma("unroll") for (int k = 0; k < 2; ++k) dst[m][k] = *(const PG8_LAS bf16x8*)(lds + PG8_SA(b, h) + aoff + m * 2048 + k * 1024); } while (0)
; #define PG8_LDB(dst, b, h) do { _Pragma("unroll") for (int n = 0; n < 2; ++n) _Pragma("unroll") for (int k = 0; k < 2; ++k) dst[n][k] = *(const PG8_LAS bf16x8*)(lds + PG8_SB(b, h) + boff + n * 2048 + k * 1024); } while (0)
; #define PG8_MMA(ai, bj, At, Bt) do { __builtin_amdgcn_s_setprio(1); _Pragma("unroll") for (int m = 0; m < 4; ++m) _Pragma("unroll") for (int n = 0; n < 2; ++n) _Pragma("unroll") for (int k = 0; k < 2; ++k) \
;         acc[ai][bj][m][n] = __builtin_amdgcn_mfma_f32_16x16x32_bf16(Bt[n][k], At[m][k], acc[ai][bj][m][n], 0, 0, 0); __builtin_amdgcn_s_setprio(0); } while (0)
; #define PG8_WAIT_V(n) asm volatile("s_waitcnt vmcnt(" #n ")" ::: "memory")
; #define PG8_WAIT_L(n) asm volatile("s_waitcnt lgkmcnt(" #n ")" ::: "memory")
; template <class Epi, class Sched, bool ALIGN_EPI = false, bool SP2 = false>
; __device__ __forceinline__ void gemm_phase(PG8_LAS unsigned char* lds, const Gemm g, const Sched& S, const Epi& E) {
;     ...
;             const bool last = (t == nt - 2);
;             const char* a1 = cA + (size_t)(t + 1) * kstep;
;             const char* a2 = last ? nA : cA + (size_t)(t + 2) * kstep; const char* b2 = last ? nB : cB + (size_t)(t + 2) * kstep;
;             const char* a3 = a2 + kstep; const char* b3 = b2 + kstep;
;             if (last && has_next) S.a_ready(nxt);
;             if constexpr (SP2) {
;             PG8_LDB(B0, 0, 0); PG8_LDB(B1, 0, 1); PG8_SCHED; PG8_LDA(At, 0, 0); PG8_STAGE(PG8_SA(1, 1), a1 + hstep, voffA);
;             PG8_WAIT_V(8); PG8_WAIT_L(0); PG8_BAR; PG8_MMA(0, 0, At, B0); PG8_MMA(0, 1, At, B1); PG8_BAR; PG8_SCHED;
;             PG8_LDA(At, 0, 1); PG8_STAGE(PG8_SB(0, 0), b2, voffB); PG8_STAGE(PG8_SB(0, 1), b2 + hstep, voffB); PG8_STAGE(PG8_SA(0, 0), a2, voffA);
;             PG8_WAIT_V(8); PG8_WAIT_L(0); PG8_BAR; PG8_MMA(1, 0, At, B0); PG8_MMA(1, 1, At, B1); PG8_BAR; PG8_SCHED;
.LBB0_220:
	s_add_u32 s18, s60, 0xfffc0080
	s_addc_u32 s38, s61, -1
	s_add_i32 s39, 0, 0x10000
	s_cmp_eq_u32 s82, 12
	s_cselect_b32 s65, s47, s38
	s_cselect_b32 s64, s78, s18
	v_add_u32_e32 v145, s39, v141
	s_cselect_b32 s57, s49, s81
	s_cselect_b32 s56, s79, s80
	s_add_i32 s18, 0, 0x14000
	ds_read_b128 v[146:149], v145
	ds_read_b128 v[150:153], v145 offset:1024
	ds_read_b128 v[154:157], v145 offset:2048
	ds_read_b128 v[158:161], v145 offset:3072
	v_add_u32_e32 v145, s18, v141
	ds_read_b128 v[162:165], v145
	ds_read_b128 v[166:169], v145 offset:1024
	ds_read_b128 v[170:173], v145 offset:2048
	ds_read_b128 v[174:177], v145 offset:3072
	v_lshl_add_u64 v[194:195], s[60:61], 0, v[136:137]
	s_add_i32 m0, s29, 0xc000
	ds_read_b128 v[178:181], v144
	ds_read_b128 v[182:185], v144 offset:1024
	ds_read_b128 v[186:189], v144 offset:2048
	ds_read_b128 v[190:193], v144 offset:3072
	ds_read_b128 v[202:205], v144 offset:4096
	ds_read_b128 v[206:209], v144 offset:5120
	ds_read_b128 v[210:213], v144 offset:6144
	ds_read_b128 v[214:217], v144 offset:7168
	global_load_lds_dwordx4 v[194:195], off
	v_lshl_add_u64 v[194:195], s[60:61], 0, v[138:139]
	s_add_i32 m0, s29, 0xe000
	s_nop 0
	global_load_lds_dwordx4 v[194:195], off
	s_waitcnt vmcnt(8)
	s_waitcnt lgkmcnt(0)
	s_barrier
	s_setprio 1
	v_mfma_f32_16x16x32_bf16 v[114:117], v[146:149], v[178:181], v[114:117]
	v_mfma_f32_16x16x32_bf16 v[114:117], v[150:153], v[182:185], v[114:117]
	v_mfma_f32_16x16x32_bf16 v[98:101], v[146:149], v[186:189], v[98:101]
	v_mfma_f32_16x16x32_bf16 v[98:101], v[150:153], v[190:193], v[98:101]
	v_mfma_f32_16x16x32_bf16 v[82:85], v[146:149], v[202:205], v[82:85]
	v_mfma_f32_16x16x32_bf16 v[82:85], v[150:153], v[206:209], v[82:85]
	v_mfma_f32_16x16x32_bf16 v[66:69], v[146:149], v[210:213], v[66:69]
	v_mfma_f32_16x16x32_bf16 v[66:69], v[150:153], v[214:217], v[66:69]
	v_mfma_f32_16x16x32_bf16 v[118:121], v[154:157], v[178:181], v[118:121]
	v_mfma_f32_16x16x32_bf16 v[118:121], v[158:161], v[182:185], v[118:121]
	v_mfma_f32_16x16x32_bf16 v[102:105], v[154:157], v[186:189], v[102:105]
	v_mfma_f32_16x16x32_bf16 v[102:105], v[158:161], v[190:193], v[102:105]
	v_mfma_f32_16x16x32_bf16 v[86:89], v[154:157], v[202:205], v[86:89]
	v_mfma_f32_16x16x32_bf16 v[86:89], v[158:161], v[206:209], v[86:89]
	v_mfma_f32_16x16x32_bf16 v[70:73], v[154:157], v[210:213], v[70:73]
	v_mfma_f32_16x16x32_bf16 v[70:73], v[158:161], v[214:217], v[70:73]
	v_mfma_f32_16x16x32_bf16 v[122:125], v[162:165], v[178:181], v[122:125]
	v_mfma_f32_16x16x32_bf16 v[122:125], v[166:169], v[182:185], v[122:125]
	v_mfma_f32_16x16x32_bf16 v[106:109], v[162:165], v[186:189], v[106:109]
	v_mfma_f32_16x16x32_bf16 v[106:109], v[166:169], v[190:193], v[106:109]
	v_mfma_f32_16x16x32_bf16 v[90:93], v[162:165], v[202:205], v[90:93]
	v_mfma_f32_16x16x32_bf16 v[90:93], v[166:169], v[206:209], v[90:93]
	v_mfma_f32_16x16x32_bf16 v[74:77], v[162:165], v[210:213], v[74:77]
	v_mfma_f32_16x16x32_bf16 v[74:77], v[166:169], v[214:217], v[74:77]
	v_mfma_f32_16x16x32_bf16 v[126:129], v[170:173], v[178:181], v[126:129]
	v_mfma_f32_16x16x32_bf16 v[126:129], v[174:177], v[182:185], v[126:129]
	v_mfma_f32_16x16x32_bf16 v[110:113], v[170:173], v[186:189], v[110:113]
	v_mfma_f32_16x16x32_bf16 v[110:113], v[174:177], v[190:193], v[110:113]
	v_mfma_f32_16x16x32_bf16 v[94:97], v[170:173], v[202:205], v[94:97]
	v_mfma_f32_16x16x32_bf16 v[94:97], v[174:177], v[206:209], v[94:97]
	v_mfma_f32_16x16x32_bf16 v[78:81], v[170:173], v[210:213], v[78:81]
	v_mfma_f32_16x16x32_bf16 v[78:81], v[174:177], v[214:217], v[78:81]
	s_setprio 0
	s_barrier
	s_add_i32 s38, s39, s27
	v_lshl_add_u64 v[194:195], s[56:57], 0, v[0:1]
	s_mov_b32 m0, s38
	ds_read_b128 v[178:181], v144 offset:16384
	ds_read_b128 v[182:185], v144 offset:17408
	ds_read_b128 v[186:189], v144 offset:18432
	ds_read_b128 v[190:193], v144 offset:19456
	ds_read_b128 v[202:205], v144 offset:20480
	ds_read_b128 v[206:209], v144 offset:21504
	ds_read_b128 v[210:213], v144 offset:22528
	ds_read_b128 v[214:217], v144 offset:23552
	global_load_lds_dwordx4 v[194:195], off
	s_add_i32 m0, s38, 0x2000
	s_add_u32 s38, s56, 0x40000
	v_lshl_add_u64 v[218:219], s[56:57], 0, v[130:131]
	s_addc_u32 s39, s57, 0
	s_add_i32 s18, s18, s27
	global_load_lds_dwordx4 v[218:219], off
	v_lshl_add_u64 v[220:221], s[38:39], 0, v[0:1]
	s_mov_b32 m0, s18
	v_lshl_add_u64 v[222:223], s[64:65], 0, v[132:133]
	global_load_lds_dwordx4 v[220:221], off
	v_lshl_add_u64 v[220:221], s[38:39], 0, v[130:131]
	s_add_i32 m0, s18, 0x2000
	s_nop 0
	global_load_lds_dwordx4 v[220:221], off
	v_lshl_add_u64 v[220:221], s[64:65], 0, v[134:135]
	s_mov_b32 m0, s29
	s_nop 0
	global_load_lds_dwordx4 v[220:221], off
	s_mov_b32 m0, s33
	s_nop 0
	global_load_lds_dwordx4 v[222:223], off
	s_waitcnt vmcnt(8)
	s_waitcnt lgkmcnt(0)
	s_barrier
; #define PG8_STAGE(bufoff, gbase, voff) do { _Pragma("unroll") for (int _i = 0; _i < 2; ++_i) \
;         __builtin_amdgcn_global_load_lds((const unsigned*)((const char*)(gbase) + (voff)[_i]), (PG8_LAS unsigned*)(lds + (bufoff) + ldsw + _i * 8192), 16, 0, 0); } while (0)
; #define PG8_LDA(dst, b, h) do { _Pragma("unroll") for (int m = 0; m < 4; ++m) _Pragma("unroll") for (int k = 0; k < 2; ++k) dst[m][k] = *(const PG8_LAS bf16x8*)(lds + PG8_SA(b, h) + aoff + m * 2048 + k * 1024); } while (0)
; #define PG8_LDB(dst, b, h) do { _Pragma("unroll") for (int n = 0; n < 2; ++n) _Pragma("unroll") for (int k = 0; k < 2; ++k) dst[n][k] = *(const PG8_LAS bf16x8*)(lds + PG8_SB(b, h) + boff + n * 2048 + k * 1024); } while (0)
; #define PG8_MMA(ai, bj, At, Bt) do { __builtin_amdgcn_s_setprio(1); _Pragma("unroll") for (int m = 0; m < 4; ++m) _Pragma("unroll") for (int n = 0; n < 2; ++n) _Pragma("unroll") for (int k = 0; k < 2; ++k) \
;         acc[ai][bj][m][n] = __builtin_amdgcn_mfma_f32_16x16x32_bf16(Bt[n][k], At[m][k], acc[ai][bj][m][n], 0, 0, 0); __builtin_amdgcn_s_setprio(0); } while (0)
; #define PG8_WAIT_V(n) asm volatile("s_waitcnt vmcnt(" #n ")" ::: "memory")
; #define PG8_WAIT_L(n) asm volatile("s_waitcnt lgkmcnt(" #n ")" ::: "memory")
; #define PG8_BAR __builtin_amdgcn_s_barrier()
; #define PG8_SCHED __builtin_amdgcn_sched_barrier(0)
; template <class Epi, class Sched, bool ALIGN_EPI = false, bool SP2 = false>
; __device__ __forceinline__ void gemm_phase(PG8_LAS unsigned char* lds, const Gemm g, const Sched& S, const Epi& E) {
;     ...
;             PG8_WAIT_V(8); PG8_WAIT_L(0); PG8_BAR; PG8_MMA(1, 0, At, B0); PG8_MMA(1, 1, At, B1); PG8_BAR; PG8_SCHED;
;             PG8_LDB(B0, 1, 0); PG8_LDB(B1, 1, 1); PG8_SCHED; PG8_LDA(At, 1, 0); PG8_STAGE(PG8_SA(0, 1), a2 + hstep, voffA);
;             PG8_WAIT_V(8); PG8_WAIT_L(0); PG8_BAR; PG8_MMA(0, 0, At, B0); PG8_MMA(0, 1, At, B1); PG8_BAR; PG8_SCHED;
	s_setprio 1
	v_mfma_f32_16x16x32_bf16 v[50:53], v[146:149], v[178:181], v[50:53]
	v_mfma_f32_16x16x32_bf16 v[50:53], v[150:153], v[182:185], v[50:53]
	v_mfma_f32_16x16x32_bf16 v[34:37], v[146:149], v[186:189], v[34:37]
	v_mfma_f32_16x16x32_bf16 v[34:37], v[150:153], v[190:193], v[34:37]
	v_mfma_f32_16x16x32_bf16 v[18:21], v[146:149], v[202:205], v[18:21]
	v_mfma_f32_16x16x32_bf16 v[18:21], v[150:153], v[206:209], v[18:21]
	v_mfma_f32_16x16x32_bf16 v[2:5], v[146:149], v[210:213], v[2:5]
	v_mfma_f32_16x16x32_bf16 v[2:5], v[150:153], v[214:217], v[2:5]
	v_mfma_f32_16x16x32_bf16 v[54:57], v[154:157], v[178:181], v[54:57]
	v_mfma_f32_16x16x32_bf16 v[54:57], v[158:161], v[182:185], v[54:57]
	v_mfma_f32_16x16x32_bf16 v[38:41], v[154:157], v[186:189], v[38:41]
	v_mfma_f32_16x16x32_bf16 v[38:41], v[158:161], v[190:193], v[38:41]
	v_mfma_f32_16x16x32_bf16 v[22:25], v[154:157], v[202:205], v[22:25]
	v_mfma_f32_16x16x32_bf16 v[22:25], v[158:161], v[206:209], v[22:25]
	v_mfma_f32_16x16x32_bf16 v[6:9], v[154:157], v[210:213], v[6:9]
	v_mfma_f32_16x16x32_bf16 v[6:9], v[158:161], v[214:217], v[6:9]
	v_mfma_f32_16x16x32_bf16 v[58:61], v[162:165], v[178:181], v[58:61]
	v_mfma_f32_16x16x32_bf16 v[58:61], v[166:169], v[182:185], v[58:61]
	v_mfma_f32_16x16x32_bf16 v[42:45], v[162:165], v[186:189], v[42:45]
	v_mfma_f32_16x16x32_bf16 v[42:45], v[166:169], v[190:193], v[42:45]
	v_mfma_f32_16x16x32_bf16 v[26:29], v[162:165], v[202:205], v[26:29]
	v_mfma_f32_16x16x32_bf16 v[26:29], v[166:169], v[206:209], v[26:29]
	v_mfma_f32_16x16x32_bf16 v[10:13], v[162:165], v[210:213], v[10:13]
	v_mfma_f32_16x16x32_bf16 v[10:13], v[166:169], v[214:217], v[10:13]
	v_mfma_f32_16x16x32_bf16 v[62:65], v[170:173], v[178:181], v[62:65]
	v_mfma_f32_16x16x32_bf16 v[62:65], v[174:177], v[182:185], v[62:65]
	v_mfma_f32_16x16x32_bf16 v[46:49], v[170:173], v[186:189], v[46:49]
	v_mfma_f32_16x16x32_bf16 v[46:49], v[174:177], v[190:193], v[46:49]
	v_mfma_f32_16x16x32_bf16 v[30:33], v[170:173], v[202:205], v[30:33]
	v_mfma_f32_16x16x32_bf16 v[30:33], v[174:177], v[206:209], v[30:33]
	v_mfma_f32_16x16x32_bf16 v[14:17], v[170:173], v[210:213], v[14:17]
	v_mfma_f32_16x16x32_bf16 v[14:17], v[174:177], v[214:217], v[14:17]
	s_setprio 0
	s_barrier
	s_add_i32 s18, 0, 0x18000
	v_add_u32_e32 v145, s18, v141
	s_add_i32 s83, 0, 0x1c000
	ds_read_b128 v[146:149], v145
	ds_read_b128 v[150:153], v145 offset:1024
	ds_read_b128 v[154:157], v145 offset:2048
	ds_read_b128 v[158:161], v145 offset:3072
	v_add_u32_e32 v145, s83, v141
	ds_read_b128 v[162:165], v145
	ds_read_b128 v[166:169], v145 offset:1024
	ds_read_b128 v[170:173], v145 offset:2048
	ds_read_b128 v[174:177], v145 offset:3072
	s_add_u32 s38, s64, 0x40000
	s_addc_u32 s39, s65, 0
	s_mov_b32 m0, s58
	v_lshl_add_u64 v[224:225], s[38:39], 0, v[134:135]
	ds_read_b128 v[178:181], v144 offset:32768
	ds_read_b128 v[182:185], v144 offset:33792
	ds_read_b128 v[186:189], v144 offset:34816
	ds_read_b128 v[190:193], v144 offset:35840
	ds_read_b128 v[202:205], v144 offset:36864
	ds_read_b128 v[206:209], v144 offset:37888
	ds_read_b128 v[210:213], v144 offset:38912
	ds_read_b128 v[214:217], v144 offset:39936
	global_load_lds_dwordx4 v[224:225], off
	v_lshl_add_u64 v[224:225], s[38:39], 0, v[132:133]
	s_mov_b32 m0, s69
	s_nop 0
	global_load_lds_dwordx4 v[224:225], off
	s_waitcnt vmcnt(8)
	s_waitcnt lgkmcnt(0)
	s_barrier
	s_setprio 1
	v_mfma_f32_16x16x32_bf16 v[114:117], v[146:149], v[178:181], v[114:117]
	v_mfma_f32_16x16x32_bf16 v[114:117], v[150:153], v[182:185], v[114:117]
	v_mfma_f32_16x16x32_bf16 v[98:101], v[146:149], v[186:189], v[98:101]
	v_mfma_f32_16x16x32_bf16 v[98:101], v[150:153], v[190:193], v[98:101]
	v_mfma_f32_16x16x32_bf16 v[82:85], v[146:149], v[202:205], v[82:85]
	v_mfma_f32_16x16x32_bf16 v[82:85], v[150:153], v[206:209], v[82:85]
	v_mfma_f32_16x16x32_bf16 v[66:69], v[146:149], v[210:213], v[66:69]
	v_mfma_f32_16x16x32_bf16 v[66:69], v[150:153], v[214:217], v[66:69]
	v_mfma_f32_16x16x32_bf16 v[118:121], v[154:157], v[178:181], v[118:121]
	v_mfma_f32_16x16x32_bf16 v[118:121], v[158:161], v[182:185], v[118:121]
	v_mfma_f32_16x16x32_bf16 v[102:105], v[154:157], v[186:189], v[102:105]
	v_mfma_f32_16x16x32_bf16 v[102:105], v[158:161], v[190:193], v[102:105]
	v_mfma_f32_16x16x32_bf16 v[86:89], v[154:157], v[202:205], v[86:89]
	v_mfma_f32_16x16x32_bf16 v[86:89], v[158:161], v[206:209], v[86:89]
	v_mfma_f32_16x16x32_bf16 v[70:73], v[154:157], v[210:213], v[70:73]
	v_mfma_f32_16x16x32_bf16 v[70:73], v[158:161], v[214:217], v[70:73]
	v_mfma_f32_16x16x32_bf16 v[122:125], v[162:165], v[178:181], v[122:125]
	v_mfma_f32_16x16x32_bf16 v[122:125], v[166:169], v[182:185], v[122:125]
	v_mfma_f32_16x16x32_bf16 v[106:109], v[162:165], v[186:189], v[106:109]
	v_mfma_f32_16x16x32_bf16 v[106:109], v[166:169], v[190:193], v[106:109]
	v_mfma_f32_16x16x32_bf16 v[90:93], v[162:165], v[202:205], v[90:93]
	v_mfma_f32_16x16x32_bf16 v[90:93], v[166:169], v[206:209], v[90:93]
	v_mfma_f32_16x16x32_bf16 v[74:77], v[162:165], v[210:213], v[74:77]
	v_mfma_f32_16x16x32_bf16 v[74:77], v[166:169], v[214:217], v[74:77]
	v_mfma_f32_16x16x32_bf16 v[126:129], v[170:173], v[178:181], v[126:129]
	v_mfma_f32_16x16x32_bf16 v[126:129], v[174:177], v[182:185], v[126:129]
	v_mfma_f32_16x16x32_bf16 v[110:113], v[170:173], v[186:189], v[110:113]
	v_mfma_f32_16x16x32_bf16 v[110:113], v[174:177], v[190:193], v[110:113]
	v_mfma_f32_16x16x32_bf16 v[94:97], v[170:173], v[202:205], v[94:97]
	v_mfma_f32_16x16x32_bf16 v[94:97], v[174:177], v[206:209], v[94:97]
	v_mfma_f32_16x16x32_bf16 v[78:81], v[170:173], v[210:213], v[78:81]
	v_mfma_f32_16x16x32_bf16 v[78:81], v[174:177], v[214:217], v[78:81]
	s_setprio 0
	s_barrier
; #define PG8_STAGE(bufoff, gbase, voff) do { _Pragma("unroll") for (int _i = 0; _i < 2; ++_i) \
;         __builtin_amdgcn_global_load_lds((const unsigned*)((const char*)(gbase) + (voff)[_i]), (PG8_LAS unsigned*)(lds + (bufoff) + ldsw + _i * 8192), 16, 0, 0); } while (0)
; #define PG8_LDA(dst, b, h) do { _Pragma("unroll") for (int m = 0; m < 4; ++m) _Pragma("unroll") for (int k = 0; k < 2; ++k) dst[m][k] = *(const PG8_LAS bf16x8*)(lds + PG8_SA(b, h) + aoff + m * 2048 + k * 1024); } while (0)
; #define PG8_MMA(ai, bj, At, Bt) do { __builtin_amdgcn_s_setprio(1); _Pragma("unroll") for (int m = 0; m < 4; ++m) _Pragma("unroll") for (int n = 0; n < 2; ++n) _Pragma("unroll") for (int k = 0; k < 2; ++k) \
;         acc[ai][bj][m][n] = __builtin_amdgcn_mfma_f32_16x16x32_bf16(Bt[n][k], At[m][k], acc[ai][bj][m][n], 0, 0, 0); __builtin_amdgcn_s_setprio(0); } while (0)
; #define PG8_WAIT_V(n) asm volatile("s_waitcnt vmcnt(" #n ")" ::: "memory")
; #define PG8_WAIT_L(n) asm volatile("s_waitcnt lgkmcnt(" #n ")" ::: "memory")
; #define PG8_BAR __builtin_amdgcn_s_barrier()
; #define PG8_SCHED __builtin_amdgcn_sched_barrier(0)
; template <class Epi, class Sched, bool ALIGN_EPI = false, bool SP2 = false>
; __device__ __forceinline__ void gemm_phase(PG8_LAS unsigned char* lds, const Gemm g, const Sched& S, const Epi& E) {
;     ...
;             PG8_LDA(At, 1, 1); PG8_STAGE(PG8_SB(1, 0), b3, voffB); PG8_STAGE(PG8_SB(1, 1), b3 + hstep, voffB); PG8_STAGE(PG8_SA(1, 0), a3, voffA);
;             PG8_WAIT_V(8); PG8_WAIT_L(0); PG8_BAR; PG8_MMA(1, 0, At, B0); PG8_MMA(1, 1, At, B1); PG8_BAR; PG8_SCHED;
;     ...
;         if constexpr (ALIGN_EPI) { if (wr == 0) PG8_BAR; }
	s_add_i32 s18, s18, s27
	v_lshl_add_u64 v[194:195], v[194:195], 0, s[30:31]
	s_mov_b32 m0, s18
	ds_read_b128 v[178:181], v144 offset:49152
	ds_read_b128 v[182:185], v144 offset:50176
	ds_read_b128 v[186:189], v144 offset:51200
	ds_read_b128 v[190:193], v144 offset:52224
	ds_read_b128 v[202:205], v144 offset:53248
	ds_read_b128 v[206:209], v144 offset:54272
	ds_read_b128 v[210:213], v144 offset:55296
	ds_read_b128 v[214:217], v144 offset:56320
	global_load_lds_dwordx4 v[194:195], off
	s_add_i32 m0, s18, 0x2000
	s_add_u32 s38, s56, 0x40080
	v_lshl_add_u64 v[194:195], v[218:219], 0, s[30:31]
	s_addc_u32 s39, s57, 0
	s_add_i32 s18, s83, s27
	global_load_lds_dwordx4 v[194:195], off
	v_lshl_add_u64 v[194:195], s[38:39], 0, v[0:1]
	s_mov_b32 m0, s18
	s_nop 0
	global_load_lds_dwordx4 v[194:195], off
	v_lshl_add_u64 v[194:195], s[38:39], 0, v[130:131]
	s_add_i32 m0, s18, 0x2000
	s_nop 0
	global_load_lds_dwordx4 v[194:195], off
	v_lshl_add_u64 v[194:195], v[220:221], 0, s[30:31]
	s_mov_b32 m0, s71
	s_nop 0
	global_load_lds_dwordx4 v[194:195], off
	v_lshl_add_u64 v[194:195], v[222:223], 0, s[30:31]
	s_mov_b32 m0, s72
	s_nop 0
	global_load_lds_dwordx4 v[194:195], off
	s_nop 0
	s_waitcnt vmcnt(8)
	s_waitcnt lgkmcnt(0)
	s_barrier
	s_setprio 1
	v_mfma_f32_16x16x32_bf16 v[50:53], v[146:149], v[178:181], v[50:53]
	v_mfma_f32_16x16x32_bf16 v[50:53], v[150:153], v[182:185], v[50:53]
	v_mfma_f32_16x16x32_bf16 v[34:37], v[146:149], v[186:189], v[34:37]
	v_mfma_f32_16x16x32_bf16 v[34:37], v[150:153], v[190:193], v[34:37]
	v_mfma_f32_16x16x32_bf16 v[18:21], v[146:149], v[202:205], v[18:21]
	v_mfma_f32_16x16x32_bf16 v[18:21], v[150:153], v[206:209], v[18:21]
	v_mfma_f32_16x16x32_bf16 v[2:5], v[146:149], v[210:213], v[2:5]
	v_mfma_f32_16x16x32_bf16 v[2:5], v[150:153], v[214:217], v[2:5]
	v_mfma_f32_16x16x32_bf16 v[54:57], v[154:157], v[178:181], v[54:57]
	v_mfma_f32_16x16x32_bf16 v[54:57], v[158:161], v[182:185], v[54:57]
	v_mfma_f32_16x16x32_bf16 v[38:41], v[154:157], v[186:189], v[38:41]
	v_mfma_f32_16x16x32_bf16 v[38:41], v[158:161], v[190:193], v[38:41]
	v_mfma_f32_16x16x32_bf16 v[22:25], v[154:157], v[202:205], v[22:25]
	v_mfma_f32_16x16x32_bf16 v[22:25], v[158:161], v[206:209], v[22:25]
	v_mfma_f32_16x16x32_bf16 v[6:9], v[154:157], v[210:213], v[6:9]
	v_mfma_f32_16x16x32_bf16 v[6:9], v[158:161], v[214:217], v[6:9]
	v_mfma_f32_16x16x32_bf16 v[58:61], v[162:165], v[178:181], v[58:61]
	v_mfma_f32_16x16x32_bf16 v[58:61], v[166:169], v[182:185], v[58:61]
	v_mfma_f32_16x16x32_bf16 v[42:45], v[162:165], v[186:189], v[42:45]
	v_mfma_f32_16x16x32_bf16 v[42:45], v[166:169], v[190:193], v[42:45]
	v_mfma_f32_16x16x32_bf16 v[26:29], v[162:165], v[202:205], v[26:29]
	v_mfma_f32_16x16x32_bf16 v[26:29], v[166:169], v[206:209], v[26:29]
	v_mfma_f32_16x16x32_bf16 v[10:13], v[162:165], v[210:213], v[10:13]
	v_mfma_f32_16x16x32_bf16 v[10:13], v[166:169], v[214:217], v[10:13]
	v_mfma_f32_16x16x32_bf16 v[62:65], v[170:173], v[178:181], v[62:65]
	v_mfma_f32_16x16x32_bf16 v[62:65], v[174:177], v[182:185], v[62:65]
	v_mfma_f32_16x16x32_bf16 v[46:49], v[170:173], v[186:189], v[46:49]
	v_mfma_f32_16x16x32_bf16 v[46:49], v[174:177], v[190:193], v[46:49]
	v_mfma_f32_16x16x32_bf16 v[30:33], v[170:173], v[202:205], v[30:33]
	v_mfma_f32_16x16x32_bf16 v[30:33], v[174:177], v[206:209], v[30:33]
	v_mfma_f32_16x16x32_bf16 v[14:17], v[170:173], v[210:213], v[14:17]
	v_mfma_f32_16x16x32_bf16 v[14:17], v[174:177], v[214:217], v[14:17]
	s_setprio 0
	s_barrier
	s_add_i32 s82, s82, 2
	s_add_u32 s60, s60, 0x100
	s_addc_u32 s61, s61, 0
	s_add_u32 s80, s80, 0x100
	s_addc_u32 s81, s81, 0
	s_cmp_gt_u32 s82, 13
	s_cbranch_scc0 .LBB0_220
	s_and_b64 vcc, exec, s[44:45]
	s_cbranch_vccz .LBB0_223
	s_barrier

; #define PG8_STAGE(bufoff, gbase, voff) do { _Pragma("unroll") for (int _i = 0; _i < 2; ++_i) \
;         __builtin_amdgcn_global_load_lds((const unsigned*)((const char*)(gbase) + (voff)[_i]), (PG8_LAS unsigned*)(lds + (bufoff) + ldsw + _i * 8192), 16, 0, 0); } while (0)
; #define PG8_LDA(dst, b, h) do { _Pragma("unroll") for (int m = 0; m < 4; ++m) _Pragma("unroll") for (int k = 0; k < 2; ++k) dst[m][k] = *(const PG8_LAS bf16x8*)(lds + PG8_SA(b, h) + aoff + m * 2048 + k * 1024); } while (0)
; #define PG8_LDB(dst, b, h) do { _Pragma("unroll") for (int n = 0; n < 2; ++n) _Pragma("unroll") for (int k = 0; k < 2; ++k) dst[n][k] = *(const PG8_LAS bf16x8*)(lds + PG8_SB(b, h) + boff + n * 2048 + k * 1024); } while (0)
; #define PG8_MMA(ai, bj, At, Bt) do { __builtin_amdgcn_s_setprio(1); _Pragma("unroll") for (int m = 0; m < 4; ++m) _Pragma("unroll") for (int n = 0; n < 2; ++n) _Pragma("unroll") for (int k = 0; k < 2; ++k) \
;         acc[ai][bj][m][n] = __builtin_amdgcn_mfma_f32_16x16x32_bf16(Bt[n][k], At[m][k], acc[ai][bj][m][n], 0, 0, 0); __builtin_amdgcn_s_setprio(0); } while (0)
; #define PG8_WAIT_V(n) asm volatile("s_waitcnt vmcnt(" #n ")" ::: "memory")
; #define PG8_WAIT_L(n) asm volatile("s_waitcnt lgkmcnt(" #n ")" ::: "memory")
; template <class Epi, class Sched, bool ALIGN_EPI = false, bool SP2 = false>
; __device__ __forceinline__ void gemm_phase(PG8_LAS unsigned char* lds, const Gemm g, const Sched& S, const Epi& E) {
;     ...
;             const bool last = (t == nt - 2);
;             const char* a1 = cA + (size_t)(t + 1) * kstep;
;             const char* a2 = last ? nA : cA + (size_t)(t + 2) * kstep; const char* b2 = last ? nB : cB + (size_t)(t + 2) * kstep;
;             const char* a3 = a2 + kstep; const char* b3 = b2 + kstep;
;             if (last && has_next) S.a_ready(nxt);
;             if constexpr (SP2) {
;             PG8_LDB(B0, 0, 0); PG8_LDB(B1, 0, 1); PG8_SCHED; PG8_LDA(At, 0, 0); PG8_STAGE(PG8_SA(1, 1), a1 + hstep, voffA);
;             PG8_WAIT_V(8); PG8_WAIT_L(0); PG8_BAR; PG8_MMA(0, 0, At, B0); PG8_MMA(0, 1, At, B1); PG8_BAR; PG8_SCHED;
;             PG8_LDA(At, 0, 1); PG8_STAGE(PG8_SB(0, 0), b2, voffB); PG8_STAGE(PG8_SB(0, 1), b2 + hstep, voffB); PG8_STAGE(PG8_SA(0, 0), a2, voffA);
;             PG8_WAIT_V(8); PG8_WAIT_L(0); PG8_BAR; PG8_MMA(1, 0, At, B0); PG8_MMA(1, 1, At, B1); PG8_BAR; PG8_SCHED;
.LBB0_274:
	s_add_i32 vcc_lo, s46, 2
	s_add_u32 s38, s48, 0x80
	s_addc_u32 s39, s49, 0
	s_add_i32 vcc_hi, 0, 0x10000
	s_cmp_eq_u32 s99, s46
	s_cselect_b32 s47, s81, s39
	s_cselect_b32 s46, s80, s38
	s_cselect_b32 s39, s83, s51
	s_cselect_b32 s38, s82, s50
	s_add_i32 s18, 0, 0x14000
	v_add_u32_e32 v142, vcc_hi, v245
	v_add_u32_e32 v158, s18, v245
	ds_read_b128 v[110:113], v142
	ds_read_b128 v[118:121], v142 offset:1024
	ds_read_b128 v[138:141], v142 offset:2048
	ds_read_b128 v[142:145], v142 offset:3072
	ds_read_b128 v[146:149], v158
	ds_read_b128 v[150:153], v158 offset:1024
	ds_read_b128 v[154:157], v158 offset:2048
	ds_read_b128 v[158:161], v158 offset:3072
	v_lshl_add_u64 v[210:211], s[48:49], 0, v[206:207]
	s_add_i32 m0, s92, 0xc000
	ds_read_b128 v[162:165], v247
	ds_read_b128 v[166:169], v247 offset:1024
	ds_read_b128 v[170:173], v247 offset:2048
	ds_read_b128 v[174:177], v247 offset:3072
	ds_read_b128 v[178:181], v247 offset:4096
	ds_read_b128 v[182:185], v247 offset:5120
	ds_read_b128 v[186:189], v247 offset:6144
	ds_read_b128 v[190:193], v247 offset:7168
	global_load_lds_dwordx4 v[210:211], off
	v_lshl_add_u64 v[210:211], s[48:49], 0, v[208:209]
	s_add_i32 m0, s92, 0xe000
	s_nop 0
	global_load_lds_dwordx4 v[210:211], off
	s_waitcnt vmcnt(8)
	s_waitcnt lgkmcnt(0)
	s_barrier
	s_setprio 1
	v_mfma_f32_16x16x32_bf16 v[130:133], v[110:113], v[162:165], v[130:133]
	v_mfma_f32_16x16x32_bf16 v[130:133], v[118:121], v[166:169], v[130:133]
	v_mfma_f32_16x16x32_bf16 v[114:117], v[110:113], v[170:173], v[114:117]
	v_mfma_f32_16x16x32_bf16 v[114:117], v[118:121], v[174:177], v[114:117]
	v_mfma_f32_16x16x32_bf16 v[94:97], v[110:113], v[178:181], v[94:97]
	v_mfma_f32_16x16x32_bf16 v[94:97], v[118:121], v[182:185], v[94:97]
	v_mfma_f32_16x16x32_bf16 v[78:81], v[110:113], v[186:189], v[78:81]
	v_mfma_f32_16x16x32_bf16 v[78:81], v[118:121], v[190:193], v[78:81]
	v_mfma_f32_16x16x32_bf16 v[134:137], v[138:141], v[162:165], v[134:137]
	v_mfma_f32_16x16x32_bf16 v[134:137], v[142:145], v[166:169], v[134:137]
	v_mfma_f32_16x16x32_bf16 v[106:109], v[138:141], v[170:173], v[106:109]
	v_mfma_f32_16x16x32_bf16 v[106:109], v[142:145], v[174:177], v[106:109]
	v_mfma_f32_16x16x32_bf16 v[90:93], v[138:141], v[178:181], v[90:93]
	v_mfma_f32_16x16x32_bf16 v[90:93], v[142:145], v[182:185], v[90:93]
	v_mfma_f32_16x16x32_bf16 v[74:77], v[138:141], v[186:189], v[74:77]
	v_mfma_f32_16x16x32_bf16 v[74:77], v[142:145], v[190:193], v[74:77]
	v_mfma_f32_16x16x32_bf16 v[126:129], v[146:149], v[162:165], v[126:129]
	v_mfma_f32_16x16x32_bf16 v[126:129], v[150:153], v[166:169], v[126:129]
	v_mfma_f32_16x16x32_bf16 v[102:105], v[146:149], v[170:173], v[102:105]
	v_mfma_f32_16x16x32_bf16 v[102:105], v[150:153], v[174:177], v[102:105]
	v_mfma_f32_16x16x32_bf16 v[86:89], v[146:149], v[178:181], v[86:89]
	v_mfma_f32_16x16x32_bf16 v[86:89], v[150:153], v[182:185], v[86:89]
	v_mfma_f32_16x16x32_bf16 v[70:73], v[146:149], v[186:189], v[70:73]
	v_mfma_f32_16x16x32_bf16 v[70:73], v[150:153], v[190:193], v[70:73]
	v_mfma_f32_16x16x32_bf16 v[122:125], v[154:157], v[162:165], v[122:125]
	v_mfma_f32_16x16x32_bf16 v[122:125], v[158:161], v[166:169], v[122:125]
	v_mfma_f32_16x16x32_bf16 v[98:101], v[154:157], v[170:173], v[98:101]
	v_mfma_f32_16x16x32_bf16 v[98:101], v[158:161], v[174:177], v[98:101]
	v_mfma_f32_16x16x32_bf16 v[82:85], v[154:157], v[178:181], v[82:85]
	v_mfma_f32_16x16x32_bf16 v[82:85], v[158:161], v[182:185], v[82:85]
	v_mfma_f32_16x16x32_bf16 v[66:69], v[154:157], v[186:189], v[66:69]
	v_mfma_f32_16x16x32_bf16 v[66:69], v[158:161], v[190:193], v[66:69]
	s_setprio 0
	s_barrier
	s_add_i32 vcc_hi, vcc_hi, s6
	v_lshl_add_u64 v[210:211], s[38:39], 0, v[0:1]
	s_mov_b32 m0, vcc_hi
	ds_read_b128 v[162:165], v247 offset:16384
	ds_read_b128 v[166:169], v247 offset:17408
	ds_read_b128 v[170:173], v247 offset:18432
	ds_read_b128 v[174:177], v247 offset:19456
	ds_read_b128 v[178:181], v247 offset:20480
	ds_read_b128 v[182:185], v247 offset:21504
	ds_read_b128 v[186:189], v247 offset:22528
	ds_read_b128 v[190:193], v247 offset:23552
	global_load_lds_dwordx4 v[210:211], off
	s_add_i32 m0, vcc_hi, 0x2000
	v_lshl_add_u64 v[212:213], s[38:39], 0, v[204:205]
	s_add_u32 s38, s38, s58
	s_addc_u32 s39, s39, 0
	s_add_i32 s18, s18, s6
	global_load_lds_dwordx4 v[212:213], off
	v_lshl_add_u64 v[214:215], s[38:39], 0, v[0:1]
	s_mov_b32 m0, s18
	v_lshl_add_u64 v[216:217], s[38:39], 0, v[204:205]
	global_load_lds_dwordx4 v[214:215], off
	s_add_i32 m0, s18, 0x2000
	v_lshl_add_u64 v[218:219], s[46:47], 0, v[194:195]
	global_load_lds_dwordx4 v[216:217], off
	s_mov_b32 m0, s92
	v_lshl_add_u64 v[220:221], s[46:47], 0, v[202:203]
	global_load_lds_dwordx4 v[218:219], off
	s_mov_b32 m0, s93
	s_nop 0
	global_load_lds_dwordx4 v[220:221], off
	s_nop 0
	s_waitcnt vmcnt(8)
	s_waitcnt lgkmcnt(0)
	s_barrier
; #define PG8_STAGE(bufoff, gbase, voff) do { _Pragma("unroll") for (int _i = 0; _i < 2; ++_i) \
;         __builtin_amdgcn_global_load_lds((const unsigned*)((const char*)(gbase) + (voff)[_i]), (PG8_LAS unsigned*)(lds + (bufoff) + ldsw + _i * 8192), 16, 0, 0); } while (0)
; #define PG8_LDA(dst, b, h) do { _Pragma("unroll") for (int m = 0; m < 4; ++m) _Pragma("unroll") for (int k = 0; k < 2; ++k) dst[m][k] = *(const PG8_LAS bf16x8*)(lds + PG8_SA(b, h) + aoff + m * 2048 + k * 1024); } while (0)
; #define PG8_LDB(dst, b, h) do { _Pragma("unroll") for (int n = 0; n < 2; ++n) _Pragma("unroll") for (int k = 0; k < 2; ++k) dst[n][k] = *(const PG8_LAS bf16x8*)(lds + PG8_SB(b, h) + boff + n * 2048 + k * 1024); } while (0)
; #define PG8_MMA(ai, bj, At, Bt) do { __builtin_amdgcn_s_setprio(1); _Pragma("unroll") for (int m = 0; m < 4; ++m) _Pragma("unroll") for (int n = 0; n < 2; ++n) _Pragma("unroll") for (int k = 0; k < 2; ++k) \
;         acc[ai][bj][m][n] = __builtin_amdgcn_mfma_f32_16x16x32_bf16(Bt[n][k], At[m][k], acc[ai][bj][m][n], 0, 0, 0); __builtin_amdgcn_s_setprio(0); } while (0)
; #define PG8_WAIT_V(n) asm volatile("s_waitcnt vmcnt(" #n ")" ::: "memory")
; #define PG8_WAIT_L(n) asm volatile("s_waitcnt lgkmcnt(" #n ")" ::: "memory")
; #define PG8_BAR __builtin_amdgcn_s_barrier()
; #define PG8_SCHED __builtin_amdgcn_sched_barrier(0)
; template <class Epi, class Sched, bool ALIGN_EPI = false, bool SP2 = false>
; __device__ __forceinline__ void gemm_phase(PG8_LAS unsigned char* lds, const Gemm g, const Sched& S, const Epi& E) {
;     ...
;             PG8_WAIT_V(8); PG8_WAIT_L(0); PG8_BAR; PG8_MMA(1, 0, At, B0); PG8_MMA(1, 1, At, B1); PG8_BAR; PG8_SCHED;
;             PG8_LDB(B0, 1, 0); PG8_LDB(B1, 1, 1); PG8_SCHED; PG8_LDA(At, 1, 0); PG8_STAGE(PG8_SA(0, 1), a2 + hstep, voffA);
;             PG8_WAIT_V(8); PG8_WAIT_L(0); PG8_BAR; PG8_MMA(0, 0, At, B0); PG8_MMA(0, 1, At, B1); PG8_BAR; PG8_SCHED;
	s_setprio 1
	v_mfma_f32_16x16x32_bf16 v[62:65], v[110:113], v[162:165], v[62:65]
	v_mfma_f32_16x16x32_bf16 v[62:65], v[118:121], v[166:169], v[62:65]
	v_mfma_f32_16x16x32_bf16 v[46:49], v[110:113], v[170:173], v[46:49]
	v_mfma_f32_16x16x32_bf16 v[46:49], v[118:121], v[174:177], v[46:49]
	v_mfma_f32_16x16x32_bf16 v[30:33], v[110:113], v[178:181], v[30:33]
	v_mfma_f32_16x16x32_bf16 v[30:33], v[118:121], v[182:185], v[30:33]
	v_mfma_f32_16x16x32_bf16 v[14:17], v[110:113], v[186:189], v[14:17]
	v_mfma_f32_16x16x32_bf16 v[14:17], v[118:121], v[190:193], v[14:17]
	v_mfma_f32_16x16x32_bf16 v[58:61], v[138:141], v[162:165], v[58:61]
	v_mfma_f32_16x16x32_bf16 v[58:61], v[142:145], v[166:169], v[58:61]
	v_mfma_f32_16x16x32_bf16 v[42:45], v[138:141], v[170:173], v[42:45]
	v_mfma_f32_16x16x32_bf16 v[42:45], v[142:145], v[174:177], v[42:45]
	v_mfma_f32_16x16x32_bf16 v[26:29], v[138:141], v[178:181], v[26:29]
	v_mfma_f32_16x16x32_bf16 v[26:29], v[142:145], v[182:185], v[26:29]
	v_mfma_f32_16x16x32_bf16 v[10:13], v[138:141], v[186:189], v[10:13]
	v_mfma_f32_16x16x32_bf16 v[10:13], v[142:145], v[190:193], v[10:13]
	v_mfma_f32_16x16x32_bf16 v[54:57], v[146:149], v[162:165], v[54:57]
	v_mfma_f32_16x16x32_bf16 v[54:57], v[150:153], v[166:169], v[54:57]
	v_mfma_f32_16x16x32_bf16 v[38:41], v[146:149], v[170:173], v[38:41]
	v_mfma_f32_16x16x32_bf16 v[38:41], v[150:153], v[174:177], v[38:41]
	v_mfma_f32_16x16x32_bf16 v[22:25], v[146:149], v[178:181], v[22:25]
	v_mfma_f32_16x16x32_bf16 v[22:25], v[150:153], v[182:185], v[22:25]
	v_mfma_f32_16x16x32_bf16 v[6:9], v[146:149], v[186:189], v[6:9]
	v_mfma_f32_16x16x32_bf16 v[6:9], v[150:153], v[190:193], v[6:9]
	v_mfma_f32_16x16x32_bf16 v[50:53], v[154:157], v[162:165], v[50:53]
	v_mfma_f32_16x16x32_bf16 v[50:53], v[158:161], v[166:169], v[50:53]
	v_mfma_f32_16x16x32_bf16 v[34:37], v[154:157], v[170:173], v[34:37]
	v_mfma_f32_16x16x32_bf16 v[34:37], v[158:161], v[174:177], v[34:37]
	v_mfma_f32_16x16x32_bf16 v[18:21], v[154:157], v[178:181], v[18:21]
	v_mfma_f32_16x16x32_bf16 v[18:21], v[158:161], v[182:185], v[18:21]
	v_mfma_f32_16x16x32_bf16 v[2:5], v[154:157], v[186:189], v[2:5]
	v_mfma_f32_16x16x32_bf16 v[2:5], v[158:161], v[190:193], v[2:5]
	s_setprio 0
	s_barrier
	s_add_i32 s18, 0, 0x18000
	s_add_i32 vcc_hi, 0, 0x1c000
	v_add_u32_e32 v142, s18, v245
	v_add_u32_e32 v158, vcc_hi, v245
	ds_read_b128 v[110:113], v142
	ds_read_b128 v[118:121], v142 offset:1024
	ds_read_b128 v[138:141], v142 offset:2048
	ds_read_b128 v[142:145], v142 offset:3072
	ds_read_b128 v[146:149], v158
	ds_read_b128 v[150:153], v158 offset:1024
	ds_read_b128 v[154:157], v158 offset:2048
	ds_read_b128 v[158:161], v158 offset:3072
	s_add_u32 s38, s46, s58
	s_addc_u32 s39, s47, 0
	s_mov_b32 m0, s94
	v_lshl_add_u64 v[222:223], s[38:39], 0, v[194:195]
	ds_read_b128 v[162:165], v247 offset:32768
	ds_read_b128 v[166:169], v247 offset:33792
	ds_read_b128 v[170:173], v247 offset:34816
	ds_read_b128 v[174:177], v247 offset:35840
	ds_read_b128 v[178:181], v247 offset:36864
	ds_read_b128 v[182:185], v247 offset:37888
	ds_read_b128 v[186:189], v247 offset:38912
	ds_read_b128 v[190:193], v247 offset:39936
	global_load_lds_dwordx4 v[222:223], off
	v_lshl_add_u64 v[222:223], s[38:39], 0, v[202:203]
	s_mov_b32 m0, s95
	s_nop 0
	global_load_lds_dwordx4 v[222:223], off
	s_nop 0
	s_waitcnt vmcnt(8)
	s_waitcnt lgkmcnt(0)
	s_barrier
	s_setprio 1
	v_mfma_f32_16x16x32_bf16 v[130:133], v[110:113], v[162:165], v[130:133]
	v_mfma_f32_16x16x32_bf16 v[130:133], v[118:121], v[166:169], v[130:133]
	v_mfma_f32_16x16x32_bf16 v[114:117], v[110:113], v[170:173], v[114:117]
	v_mfma_f32_16x16x32_bf16 v[114:117], v[118:121], v[174:177], v[114:117]
	v_mfma_f32_16x16x32_bf16 v[94:97], v[110:113], v[178:181], v[94:97]
	v_mfma_f32_16x16x32_bf16 v[94:97], v[118:121], v[182:185], v[94:97]
	v_mfma_f32_16x16x32_bf16 v[78:81], v[110:113], v[186:189], v[78:81]
	v_mfma_f32_16x16x32_bf16 v[78:81], v[118:121], v[190:193], v[78:81]
	v_mfma_f32_16x16x32_bf16 v[134:137], v[138:141], v[162:165], v[134:137]
	v_mfma_f32_16x16x32_bf16 v[134:137], v[142:145], v[166:169], v[134:137]
	v_mfma_f32_16x16x32_bf16 v[106:109], v[138:141], v[170:173], v[106:109]
	v_mfma_f32_16x16x32_bf16 v[106:109], v[142:145], v[174:177], v[106:109]
	v_mfma_f32_16x16x32_bf16 v[90:93], v[138:141], v[178:181], v[90:93]
	v_mfma_f32_16x16x32_bf16 v[90:93], v[142:145], v[182:185], v[90:93]
	v_mfma_f32_16x16x32_bf16 v[74:77], v[138:141], v[186:189], v[74:77]
	v_mfma_f32_16x16x32_bf16 v[74:77], v[142:145], v[190:193], v[74:77]
	v_mfma_f32_16x16x32_bf16 v[126:129], v[146:149], v[162:165], v[126:129]
	v_mfma_f32_16x16x32_bf16 v[126:129], v[150:153], v[166:169], v[126:129]
	v_mfma_f32_16x16x32_bf16 v[102:105], v[146:149], v[170:173], v[102:105]
	v_mfma_f32_16x16x32_bf16 v[102:105], v[150:153], v[174:177], v[102:105]
	v_mfma_f32_16x16x32_bf16 v[86:89], v[146:149], v[178:181], v[86:89]
	v_mfma_f32_16x16x32_bf16 v[86:89], v[150:153], v[182:185], v[86:89]
	v_mfma_f32_16x16x32_bf16 v[70:73], v[146:149], v[186:189], v[70:73]
	v_mfma_f32_16x16x32_bf16 v[70:73], v[150:153], v[190:193], v[70:73]
	v_mfma_f32_16x16x32_bf16 v[122:125], v[154:157], v[162:165], v[122:125]
	v_mfma_f32_16x16x32_bf16 v[122:125], v[158:161], v[166:169], v[122:125]
	v_mfma_f32_16x16x32_bf16 v[98:101], v[154:157], v[170:173], v[98:101]
	v_mfma_f32_16x16x32_bf16 v[98:101], v[158:161], v[174:177], v[98:101]
	v_mfma_f32_16x16x32_bf16 v[82:85], v[154:157], v[178:181], v[82:85]
	v_mfma_f32_16x16x32_bf16 v[82:85], v[158:161], v[182:185], v[82:85]
	v_mfma_f32_16x16x32_bf16 v[66:69], v[154:157], v[186:189], v[66:69]
	v_mfma_f32_16x16x32_bf16 v[66:69], v[158:161], v[190:193], v[66:69]
	s_setprio 0
	s_barrier
; #define PG8_STAGE(bufoff, gbase, voff) do { _Pragma("unroll") for (int _i = 0; _i < 2; ++_i) \
;         __builtin_amdgcn_global_load_lds((const unsigned*)((const char*)(gbase) + (voff)[_i]), (PG8_LAS unsigned*)(lds + (bufoff) + ldsw + _i * 8192), 16, 0, 0); } while (0)
; #define PG8_LDA(dst, b, h) do { _Pragma("unroll") for (int m = 0; m < 4; ++m) _Pragma("unroll") for (int k = 0; k < 2; ++k) dst[m][k] = *(const PG8_LAS bf16x8*)(lds + PG8_SA(b, h) + aoff + m * 2048 + k * 1024); } while (0)
; #define PG8_MMA(ai, bj, At, Bt) do { __builtin_amdgcn_s_setprio(1); _Pragma("unroll") for (int m = 0; m < 4; ++m) _Pragma("unroll") for (int n = 0; n < 2; ++n) _Pragma("unroll") for (int k = 0; k < 2; ++k) \
;         acc[ai][bj][m][n] = __builtin_amdgcn_mfma_f32_16x16x32_bf16(Bt[n][k], At[m][k], acc[ai][bj][m][n], 0, 0, 0); __builtin_amdgcn_s_setprio(0); } while (0)
; #define PG8_WAIT_V(n) asm volatile("s_waitcnt vmcnt(" #n ")" ::: "memory")
; #define PG8_WAIT_L(n) asm volatile("s_waitcnt lgkmcnt(" #n ")" ::: "memory")
; #define PG8_BAR __builtin_amdgcn_s_barrier()
; #define PG8_SCHED __builtin_amdgcn_sched_barrier(0)
; template <class Epi, class Sched, bool ALIGN_EPI = false, bool SP2 = false>
; __device__ __forceinline__ void gemm_phase(PG8_LAS unsigned char* lds, const Gemm g, const Sched& S, const Epi& E) {
;     ...
;             PG8_LDA(At, 1, 1); PG8_STAGE(PG8_SB(1, 0), b3, voffB); PG8_STAGE(PG8_SB(1, 1), b3 + hstep, voffB); PG8_STAGE(PG8_SA(1, 0), a3, voffA);
;             PG8_WAIT_V(8); PG8_WAIT_L(0); PG8_BAR; PG8_MMA(1, 0, At, B0); PG8_MMA(1, 1, At, B1); PG8_BAR; PG8_SCHED;
;     ...
;         if constexpr (ALIGN_EPI) { if (wr == 0) PG8_BAR; }
	s_add_i32 s18, s18, s6
	v_lshl_add_u64 v[210:211], v[210:211], 0, s[30:31]
	s_mov_b32 m0, s18
	ds_read_b128 v[162:165], v247 offset:49152
	ds_read_b128 v[166:169], v247 offset:50176
	ds_read_b128 v[170:173], v247 offset:51200
	ds_read_b128 v[174:177], v247 offset:52224
	ds_read_b128 v[178:181], v247 offset:53248
	ds_read_b128 v[182:185], v247 offset:54272
	ds_read_b128 v[186:189], v247 offset:55296
	ds_read_b128 v[190:193], v247 offset:56320
	global_load_lds_dwordx4 v[210:211], off
	v_lshl_add_u64 v[210:211], v[212:213], 0, s[30:31]
	s_add_i32 m0, s18, 0x2000
	s_add_i32 s18, vcc_hi, s6
	global_load_lds_dwordx4 v[210:211], off
	v_lshl_add_u64 v[210:211], v[214:215], 0, s[30:31]
	s_mov_b32 m0, s18
	s_nop 0
	global_load_lds_dwordx4 v[210:211], off
	v_lshl_add_u64 v[210:211], v[216:217], 0, s[30:31]
	s_add_i32 m0, s18, 0x2000
	s_nop 0
	global_load_lds_dwordx4 v[210:211], off
	v_lshl_add_u64 v[210:211], v[218:219], 0, s[30:31]
	s_mov_b32 m0, s97
	s_nop 0
	global_load_lds_dwordx4 v[210:211], off
	v_lshl_add_u64 v[210:211], v[220:221], 0, s[30:31]
	s_mov_b32 m0, s98
	s_nop 0
	global_load_lds_dwordx4 v[210:211], off
	s_waitcnt vmcnt(8)
	s_waitcnt lgkmcnt(0)
	s_barrier
	s_setprio 1
	v_mfma_f32_16x16x32_bf16 v[62:65], v[110:113], v[162:165], v[62:65]
	v_mfma_f32_16x16x32_bf16 v[62:65], v[118:121], v[166:169], v[62:65]
	v_mfma_f32_16x16x32_bf16 v[46:49], v[110:113], v[170:173], v[46:49]
	v_mfma_f32_16x16x32_bf16 v[46:49], v[118:121], v[174:177], v[46:49]
	v_mfma_f32_16x16x32_bf16 v[30:33], v[110:113], v[178:181], v[30:33]
	v_mfma_f32_16x16x32_bf16 v[30:33], v[118:121], v[182:185], v[30:33]
	v_mfma_f32_16x16x32_bf16 v[14:17], v[110:113], v[186:189], v[14:17]
	v_mfma_f32_16x16x32_bf16 v[14:17], v[118:121], v[190:193], v[14:17]
	v_mfma_f32_16x16x32_bf16 v[58:61], v[138:141], v[162:165], v[58:61]
	v_mfma_f32_16x16x32_bf16 v[58:61], v[142:145], v[166:169], v[58:61]
	v_mfma_f32_16x16x32_bf16 v[42:45], v[138:141], v[170:173], v[42:45]
	v_mfma_f32_16x16x32_bf16 v[42:45], v[142:145], v[174:177], v[42:45]
	v_mfma_f32_16x16x32_bf16 v[26:29], v[138:141], v[178:181], v[26:29]
	v_mfma_f32_16x16x32_bf16 v[26:29], v[142:145], v[182:185], v[26:29]
	v_mfma_f32_16x16x32_bf16 v[10:13], v[138:141], v[186:189], v[10:13]
	v_mfma_f32_16x16x32_bf16 v[10:13], v[142:145], v[190:193], v[10:13]
	v_mfma_f32_16x16x32_bf16 v[54:57], v[146:149], v[162:165], v[54:57]
	v_mfma_f32_16x16x32_bf16 v[54:57], v[150:153], v[166:169], v[54:57]
	v_mfma_f32_16x16x32_bf16 v[38:41], v[146:149], v[170:173], v[38:41]
	v_mfma_f32_16x16x32_bf16 v[38:41], v[150:153], v[174:177], v[38:41]
	v_mfma_f32_16x16x32_bf16 v[22:25], v[146:149], v[178:181], v[22:25]
	v_mfma_f32_16x16x32_bf16 v[22:25], v[150:153], v[182:185], v[22:25]
	v_mfma_f32_16x16x32_bf16 v[6:9], v[146:149], v[186:189], v[6:9]
	v_mfma_f32_16x16x32_bf16 v[6:9], v[150:153], v[190:193], v[6:9]
	v_mfma_f32_16x16x32_bf16 v[50:53], v[154:157], v[162:165], v[50:53]
	v_mfma_f32_16x16x32_bf16 v[50:53], v[158:161], v[166:169], v[50:53]
	v_mfma_f32_16x16x32_bf16 v[34:37], v[154:157], v[170:173], v[34:37]
	v_mfma_f32_16x16x32_bf16 v[34:37], v[158:161], v[174:177], v[34:37]
	v_mfma_f32_16x16x32_bf16 v[18:21], v[154:157], v[178:181], v[18:21]
	v_mfma_f32_16x16x32_bf16 v[18:21], v[158:161], v[182:185], v[18:21]
	v_mfma_f32_16x16x32_bf16 v[2:5], v[154:157], v[186:189], v[2:5]
	v_mfma_f32_16x16x32_bf16 v[2:5], v[158:161], v[190:193], v[2:5]
	s_setprio 0
	s_barrier
	s_add_u32 s48, s48, 0x100
	s_addc_u32 s49, s49, 0
	s_add_u32 s50, s50, 0x100
	s_addc_u32 s51, s51, 0
	s_cmp_ge_u32 vcc_lo, s96
	s_mov_b32 s46, vcc_lo
	s_cbranch_scc0 .LBB0_274
	s_and_b64 vcc, exec, s[72:73]
	s_cbranch_vccz .LBB0_277
	s_barrier

; #define PG8_STAGE(bufoff, gbase, voff) do { _Pragma("unroll") for (int _i = 0; _i < 2; ++_i) \
;         __builtin_amdgcn_global_load_lds((const unsigned*)((const char*)(gbase) + (voff)[_i]), (PG8_LAS unsigned*)(lds + (bufoff) + ldsw + _i * 8192), 16, 0, 0); } while (0)
; #define PG8_LDA(dst, b, h) do { _Pragma("unroll") for (int m = 0; m < 4; ++m) _Pragma("unroll") for (int k = 0; k < 2; ++k) dst[m][k] = *(const PG8_LAS bf16x8*)(lds + PG8_SA(b, h) + aoff + m * 2048 + k * 1024); } while (0)
; #define PG8_LDB(dst, b, h) do { _Pragma("unroll") for (int n = 0; n < 2; ++n) _Pragma("unroll") for (int k = 0; k < 2; ++k) dst[n][k] = *(const PG8_LAS bf16x8*)(lds + PG8_SB(b, h) + boff + n * 2048 + k * 1024); } while (0)
; #define PG8_MMA(ai, bj, At, Bt) do { __builtin_amdgcn_s_setprio(1); _Pragma("unroll") for (int m = 0; m < 4; ++m) _Pragma("unroll") for (int n = 0; n < 2; ++n) _Pragma("unroll") for (int k = 0; k < 2; ++k) \
;         acc[ai][bj][m][n] = __builtin_amdgcn_mfma_f32_16x16x32_bf16(Bt[n][k], At[m][k], acc[ai][bj][m][n], 0, 0, 0); __builtin_amdgcn_s_setprio(0); } while (0)
; #define PG8_WAIT_V(n) asm volatile("s_waitcnt vmcnt(" #n ")" ::: "memory")
; #define PG8_WAIT_L(n) asm volatile("s_waitcnt lgkmcnt(" #n ")" ::: "memory")
; template <class Epi, class Sched, bool ALIGN_EPI = false, bool SP2 = false>
; __device__ __forceinline__ void gemm_phase(PG8_LAS unsigned char* lds, const Gemm g, const Sched& S, const Epi& E) {
;     ...
;             const bool last = (t == nt - 2);
;             const char* a1 = cA + (size_t)(t + 1) * kstep;
;             const char* a2 = last ? nA : cA + (size_t)(t + 2) * kstep; const char* b2 = last ? nB : cB + (size_t)(t + 2) * kstep;
;             const char* a3 = a2 + kstep; const char* b3 = b2 + kstep;
;             if (last && has_next) S.a_ready(nxt);
;             if constexpr (SP2) {
;             PG8_LDB(B0, 0, 0); PG8_LDB(B1, 0, 1); PG8_SCHED; PG8_LDA(At, 0, 0); PG8_STAGE(PG8_SA(1, 1), a1 + hstep, voffA);
;             PG8_WAIT_V(8); PG8_WAIT_L(0); PG8_BAR; PG8_MMA(0, 0, At, B0); PG8_MMA(0, 1, At, B1); PG8_BAR; PG8_SCHED;
;             PG8_LDA(At, 0, 1); PG8_STAGE(PG8_SB(0, 0), b2, voffB); PG8_STAGE(PG8_SB(0, 1), b2 + hstep, voffB); PG8_STAGE(PG8_SA(0, 0), a2, voffA);
;             PG8_WAIT_V(8); PG8_WAIT_L(0); PG8_BAR; PG8_MMA(1, 0, At, B0); PG8_MMA(1, 1, At, B1); PG8_BAR; PG8_SCHED;
.LBB0_408:
	s_add_u32 s38, s48, 0xfffc0080
	s_addc_u32 s39, s49, -1
	s_add_i32 s85, 0, 0x10000
	s_cmp_eq_u32 s84, 12
	s_cselect_b32 s73, s21, s39
	s_cselect_b32 s72, s27, s38
	v_add_u32_e32 v0, s85, v167
	s_cselect_b32 s47, s29, s69
	s_cselect_b32 s46, s33, s53
	s_add_i32 s38, 0, 0x14000
	ds_read_b128 v[142:145], v0
	ds_read_b128 v[146:149], v0 offset:1024
	ds_read_b128 v[150:153], v0 offset:2048
	ds_read_b128 v[154:157], v0 offset:3072
	v_add_u32_e32 v0, s38, v167
	ds_read_b128 v[158:161], v0
	ds_read_b128 v[162:165], v0 offset:1024
	ds_read_b128 v[172:175], v0 offset:2048
	ds_read_b128 v[176:179], v0 offset:3072
	v_lshl_add_u64 v[218:219], s[48:49], 0, v[138:139]
	s_add_i32 m0, s76, 0xc000
	ds_read_b128 v[180:183], v170
	ds_read_b128 v[184:187], v170 offset:1024
	ds_read_b128 v[188:191], v170 offset:2048
	ds_read_b128 v[192:195], v170 offset:3072
	ds_read_b128 v[202:205], v170 offset:4096
	ds_read_b128 v[206:209], v170 offset:5120
	ds_read_b128 v[210:213], v170 offset:6144
	ds_read_b128 v[214:217], v170 offset:7168
	global_load_lds_dwordx4 v[218:219], off
	v_lshl_add_u64 v[218:219], s[48:49], 0, v[140:141]
	s_add_i32 m0, s76, 0xe000
	s_nop 0
	global_load_lds_dwordx4 v[218:219], off
	s_nop 0
	s_waitcnt vmcnt(8)
	s_waitcnt lgkmcnt(0)
	s_barrier
	s_setprio 1
	v_mfma_f32_16x16x32_bf16 v[122:125], v[142:145], v[180:183], v[122:125]
	v_mfma_f32_16x16x32_bf16 v[122:125], v[146:149], v[184:187], v[122:125]
	v_mfma_f32_16x16x32_bf16 v[106:109], v[142:145], v[188:191], v[106:109]
	v_mfma_f32_16x16x32_bf16 v[106:109], v[146:149], v[192:195], v[106:109]
	v_mfma_f32_16x16x32_bf16 v[90:93], v[142:145], v[202:205], v[90:93]
	v_mfma_f32_16x16x32_bf16 v[90:93], v[146:149], v[206:209], v[90:93]
	v_mfma_f32_16x16x32_bf16 v[74:77], v[142:145], v[210:213], v[74:77]
	v_mfma_f32_16x16x32_bf16 v[74:77], v[146:149], v[214:217], v[74:77]
	v_mfma_f32_16x16x32_bf16 v[126:129], v[150:153], v[180:183], v[126:129]
	v_mfma_f32_16x16x32_bf16 v[126:129], v[154:157], v[184:187], v[126:129]
	v_mfma_f32_16x16x32_bf16 v[110:113], v[150:153], v[188:191], v[110:113]
	v_mfma_f32_16x16x32_bf16 v[110:113], v[154:157], v[192:195], v[110:113]
	v_mfma_f32_16x16x32_bf16 v[94:97], v[150:153], v[202:205], v[94:97]
	v_mfma_f32_16x16x32_bf16 v[94:97], v[154:157], v[206:209], v[94:97]
	v_mfma_f32_16x16x32_bf16 v[78:81], v[150:153], v[210:213], v[78:81]
	v_mfma_f32_16x16x32_bf16 v[78:81], v[154:157], v[214:217], v[78:81]
	v_mfma_f32_16x16x32_bf16 v[114:117], v[158:161], v[180:183], v[114:117]
	v_mfma_f32_16x16x32_bf16 v[114:117], v[162:165], v[184:187], v[114:117]
	v_mfma_f32_16x16x32_bf16 v[98:101], v[158:161], v[188:191], v[98:101]
	v_mfma_f32_16x16x32_bf16 v[98:101], v[162:165], v[192:195], v[98:101]
	v_mfma_f32_16x16x32_bf16 v[82:85], v[158:161], v[202:205], v[82:85]
	v_mfma_f32_16x16x32_bf16 v[82:85], v[162:165], v[206:209], v[82:85]
	v_mfma_f32_16x16x32_bf16 v[66:69], v[158:161], v[210:213], v[66:69]
	v_mfma_f32_16x16x32_bf16 v[66:69], v[162:165], v[214:217], v[66:69]
	v_mfma_f32_16x16x32_bf16 v[118:121], v[172:175], v[180:183], v[118:121]
	v_mfma_f32_16x16x32_bf16 v[118:121], v[176:179], v[184:187], v[118:121]
	v_mfma_f32_16x16x32_bf16 v[102:105], v[172:175], v[188:191], v[102:105]
	v_mfma_f32_16x16x32_bf16 v[102:105], v[176:179], v[192:195], v[102:105]
	v_mfma_f32_16x16x32_bf16 v[86:89], v[172:175], v[202:205], v[86:89]
	v_mfma_f32_16x16x32_bf16 v[86:89], v[176:179], v[206:209], v[86:89]
	v_mfma_f32_16x16x32_bf16 v[70:73], v[172:175], v[210:213], v[70:73]
	v_mfma_f32_16x16x32_bf16 v[70:73], v[176:179], v[214:217], v[70:73]
	s_setprio 0
	s_barrier
	s_add_i32 s39, s85, s75
	v_lshl_add_u64 v[218:219], s[46:47], 0, v[134:135]
	s_mov_b32 m0, s39
	ds_read_b128 v[180:183], v170 offset:16384
	ds_read_b128 v[184:187], v170 offset:17408
	ds_read_b128 v[188:191], v170 offset:18432
	ds_read_b128 v[192:195], v170 offset:19456
	ds_read_b128 v[202:205], v170 offset:20480
	ds_read_b128 v[206:209], v170 offset:21504
	ds_read_b128 v[210:213], v170 offset:22528
	ds_read_b128 v[214:217], v170 offset:23552
	global_load_lds_dwordx4 v[218:219], off
	s_add_i32 m0, s39, 0x2000
	s_add_u32 s92, s46, 0x40000
	v_lshl_add_u64 v[220:221], s[46:47], 0, v[130:131]
	s_addc_u32 s93, s47, 0
	s_add_i32 s38, s38, s75
	global_load_lds_dwordx4 v[220:221], off
	v_lshl_add_u64 v[222:223], s[92:93], 0, v[134:135]
	s_mov_b32 m0, s38
	v_lshl_add_u64 v[224:225], s[72:73], 0, v[132:133]
	global_load_lds_dwordx4 v[222:223], off
	v_lshl_add_u64 v[222:223], s[92:93], 0, v[130:131]
	s_add_i32 m0, s38, 0x2000
	s_nop 0
	global_load_lds_dwordx4 v[222:223], off
	v_lshl_add_u64 v[222:223], s[72:73], 0, v[136:137]
	s_mov_b32 m0, s76
	s_nop 0
	global_load_lds_dwordx4 v[222:223], off
	s_mov_b32 m0, s77
	s_nop 0
	global_load_lds_dwordx4 v[224:225], off
	s_waitcnt vmcnt(8)
	s_waitcnt lgkmcnt(0)
	s_barrier
; #define PG8_STAGE(bufoff, gbase, voff) do { _Pragma("unroll") for (int _i = 0; _i < 2; ++_i) \
;         __builtin_amdgcn_global_load_lds((const unsigned*)((const char*)(gbase) + (voff)[_i]), (PG8_LAS unsigned*)(lds + (bufoff) + ldsw + _i * 8192), 16, 0, 0); } while (0)
; #define PG8_LDA(dst, b, h) do { _Pragma("unroll") for (int m = 0; m < 4; ++m) _Pragma("unroll") for (int k = 0; k < 2; ++k) dst[m][k] = *(const PG8_LAS bf16x8*)(lds + PG8_SA(b, h) + aoff + m * 2048 + k * 1024); } while (0)
; #define PG8_LDB(dst, b, h) do { _Pragma("unroll") for (int n = 0; n < 2; ++n) _Pragma("unroll") for (int k = 0; k < 2; ++k) dst[n][k] = *(const PG8_LAS bf16x8*)(lds + PG8_SB(b, h) + boff + n * 2048 + k * 1024); } while (0)
; #define PG8_MMA(ai, bj, At, Bt) do { __builtin_amdgcn_s_setprio(1); _Pragma("unroll") for (int m = 0; m < 4; ++m) _Pragma("unroll") for (int n = 0; n < 2; ++n) _Pragma("unroll") for (int k = 0; k < 2; ++k) \
;         acc[ai][bj][m][n] = __builtin_amdgcn_mfma_f32_16x16x32_bf16(Bt[n][k], At[m][k], acc[ai][bj][m][n], 0, 0, 0); __builtin_amdgcn_s_setprio(0); } while (0)
; #define PG8_WAIT_V(n) asm volatile("s_waitcnt vmcnt(" #n ")" ::: "memory")
; #define PG8_WAIT_L(n) asm volatile("s_waitcnt lgkmcnt(" #n ")" ::: "memory")
; #define PG8_BAR __builtin_amdgcn_s_barrier()
; #define PG8_SCHED __builtin_amdgcn_sched_barrier(0)
; template <class Epi, class Sched, bool ALIGN_EPI = false, bool SP2 = false>
; __device__ __forceinline__ void gemm_phase(PG8_LAS unsigned char* lds, const Gemm g, const Sched& S, const Epi& E) {
;     ...
;             PG8_WAIT_V(8); PG8_WAIT_L(0); PG8_BAR; PG8_MMA(1, 0, At, B0); PG8_MMA(1, 1, At, B1); PG8_BAR; PG8_SCHED;
;             PG8_LDB(B0, 1, 0); PG8_LDB(B1, 1, 1); PG8_SCHED; PG8_LDA(At, 1, 0); PG8_STAGE(PG8_SA(0, 1), a2 + hstep, voffA);
;             PG8_WAIT_V(8); PG8_WAIT_L(0); PG8_BAR; PG8_MMA(0, 0, At, B0); PG8_MMA(0, 1, At, B1); PG8_BAR; PG8_SCHED;
	s_setprio 1
	v_mfma_f32_16x16x32_bf16 v[58:61], v[142:145], v[180:183], v[58:61]
	v_mfma_f32_16x16x32_bf16 v[58:61], v[146:149], v[184:187], v[58:61]
	v_mfma_f32_16x16x32_bf16 v[42:45], v[142:145], v[188:191], v[42:45]
	v_mfma_f32_16x16x32_bf16 v[42:45], v[146:149], v[192:195], v[42:45]
	v_mfma_f32_16x16x32_bf16 v[26:29], v[142:145], v[202:205], v[26:29]
	v_mfma_f32_16x16x32_bf16 v[26:29], v[146:149], v[206:209], v[26:29]
	v_mfma_f32_16x16x32_bf16 v[10:13], v[142:145], v[210:213], v[10:13]
	v_mfma_f32_16x16x32_bf16 v[10:13], v[146:149], v[214:217], v[10:13]
	v_mfma_f32_16x16x32_bf16 v[62:65], v[150:153], v[180:183], v[62:65]
	v_mfma_f32_16x16x32_bf16 v[62:65], v[154:157], v[184:187], v[62:65]
	v_mfma_f32_16x16x32_bf16 v[46:49], v[150:153], v[188:191], v[46:49]
	v_mfma_f32_16x16x32_bf16 v[46:49], v[154:157], v[192:195], v[46:49]
	v_mfma_f32_16x16x32_bf16 v[30:33], v[150:153], v[202:205], v[30:33]
	v_mfma_f32_16x16x32_bf16 v[30:33], v[154:157], v[206:209], v[30:33]
	v_mfma_f32_16x16x32_bf16 v[14:17], v[150:153], v[210:213], v[14:17]
	v_mfma_f32_16x16x32_bf16 v[14:17], v[154:157], v[214:217], v[14:17]
	v_mfma_f32_16x16x32_bf16 v[50:53], v[158:161], v[180:183], v[50:53]
	v_mfma_f32_16x16x32_bf16 v[50:53], v[162:165], v[184:187], v[50:53]
	v_mfma_f32_16x16x32_bf16 v[34:37], v[158:161], v[188:191], v[34:37]
	v_mfma_f32_16x16x32_bf16 v[34:37], v[162:165], v[192:195], v[34:37]
	v_mfma_f32_16x16x32_bf16 v[18:21], v[158:161], v[202:205], v[18:21]
	v_mfma_f32_16x16x32_bf16 v[18:21], v[162:165], v[206:209], v[18:21]
	v_mfma_f32_16x16x32_bf16 v[2:5], v[158:161], v[210:213], v[2:5]
	v_mfma_f32_16x16x32_bf16 v[2:5], v[162:165], v[214:217], v[2:5]
	v_mfma_f32_16x16x32_bf16 v[54:57], v[172:175], v[180:183], v[54:57]
	v_mfma_f32_16x16x32_bf16 v[54:57], v[176:179], v[184:187], v[54:57]
	v_mfma_f32_16x16x32_bf16 v[38:41], v[172:175], v[188:191], v[38:41]
	v_mfma_f32_16x16x32_bf16 v[38:41], v[176:179], v[192:195], v[38:41]
	v_mfma_f32_16x16x32_bf16 v[22:25], v[172:175], v[202:205], v[22:25]
	v_mfma_f32_16x16x32_bf16 v[22:25], v[176:179], v[206:209], v[22:25]
	v_mfma_f32_16x16x32_bf16 v[6:9], v[172:175], v[210:213], v[6:9]
	v_mfma_f32_16x16x32_bf16 v[6:9], v[176:179], v[214:217], v[6:9]
	s_setprio 0
	s_barrier
	s_add_i32 s38, 0, 0x18000
	v_add_u32_e32 v0, s38, v167
	s_add_i32 s39, 0, 0x1c000
	ds_read_b128 v[142:145], v0
	ds_read_b128 v[146:149], v0 offset:1024
	ds_read_b128 v[150:153], v0 offset:2048
	ds_read_b128 v[154:157], v0 offset:3072
	v_add_u32_e32 v0, s39, v167
	ds_read_b128 v[158:161], v0
	ds_read_b128 v[162:165], v0 offset:1024
	ds_read_b128 v[172:175], v0 offset:2048
	ds_read_b128 v[176:179], v0 offset:3072
	s_add_u32 s72, s72, 0x40000
	s_addc_u32 s73, s73, 0
	s_mov_b32 m0, s78
	v_lshl_add_u64 v[226:227], s[72:73], 0, v[136:137]
	ds_read_b128 v[180:183], v170 offset:32768
	ds_read_b128 v[184:187], v170 offset:33792
	ds_read_b128 v[188:191], v170 offset:34816
	ds_read_b128 v[192:195], v170 offset:35840
	ds_read_b128 v[202:205], v170 offset:36864
	ds_read_b128 v[206:209], v170 offset:37888
	ds_read_b128 v[210:213], v170 offset:38912
	ds_read_b128 v[214:217], v170 offset:39936
	global_load_lds_dwordx4 v[226:227], off
	v_lshl_add_u64 v[226:227], s[72:73], 0, v[132:133]
	s_mov_b32 m0, s79
	s_nop 0
	global_load_lds_dwordx4 v[226:227], off
	s_waitcnt vmcnt(8)
	s_waitcnt lgkmcnt(0)
	s_barrier
	s_setprio 1
	v_mfma_f32_16x16x32_bf16 v[122:125], v[142:145], v[180:183], v[122:125]
	v_mfma_f32_16x16x32_bf16 v[122:125], v[146:149], v[184:187], v[122:125]
	v_mfma_f32_16x16x32_bf16 v[106:109], v[142:145], v[188:191], v[106:109]
	v_mfma_f32_16x16x32_bf16 v[106:109], v[146:149], v[192:195], v[106:109]
	v_mfma_f32_16x16x32_bf16 v[90:93], v[142:145], v[202:205], v[90:93]
	v_mfma_f32_16x16x32_bf16 v[90:93], v[146:149], v[206:209], v[90:93]
	v_mfma_f32_16x16x32_bf16 v[74:77], v[142:145], v[210:213], v[74:77]
	v_mfma_f32_16x16x32_bf16 v[74:77], v[146:149], v[214:217], v[74:77]
	v_mfma_f32_16x16x32_bf16 v[126:129], v[150:153], v[180:183], v[126:129]
	v_mfma_f32_16x16x32_bf16 v[126:129], v[154:157], v[184:187], v[126:129]
	v_mfma_f32_16x16x32_bf16 v[110:113], v[150:153], v[188:191], v[110:113]
	v_mfma_f32_16x16x32_bf16 v[110:113], v[154:157], v[192:195], v[110:113]
	v_mfma_f32_16x16x32_bf16 v[94:97], v[150:153], v[202:205], v[94:97]
	v_mfma_f32_16x16x32_bf16 v[94:97], v[154:157], v[206:209], v[94:97]
	v_mfma_f32_16x16x32_bf16 v[78:81], v[150:153], v[210:213], v[78:81]
	v_mfma_f32_16x16x32_bf16 v[78:81], v[154:157], v[214:217], v[78:81]
	v_mfma_f32_16x16x32_bf16 v[114:117], v[158:161], v[180:183], v[114:117]
	v_mfma_f32_16x16x32_bf16 v[114:117], v[162:165], v[184:187], v[114:117]
	v_mfma_f32_16x16x32_bf16 v[98:101], v[158:161], v[188:191], v[98:101]
	v_mfma_f32_16x16x32_bf16 v[98:101], v[162:165], v[192:195], v[98:101]
	v_mfma_f32_16x16x32_bf16 v[82:85], v[158:161], v[202:205], v[82:85]
	v_mfma_f32_16x16x32_bf16 v[82:85], v[162:165], v[206:209], v[82:85]
	v_mfma_f32_16x16x32_bf16 v[66:69], v[158:161], v[210:213], v[66:69]
	v_mfma_f32_16x16x32_bf16 v[66:69], v[162:165], v[214:217], v[66:69]
	v_mfma_f32_16x16x32_bf16 v[118:121], v[172:175], v[180:183], v[118:121]
	v_mfma_f32_16x16x32_bf16 v[118:121], v[176:179], v[184:187], v[118:121]
	v_mfma_f32_16x16x32_bf16 v[102:105], v[172:175], v[188:191], v[102:105]
	v_mfma_f32_16x16x32_bf16 v[102:105], v[176:179], v[192:195], v[102:105]
	v_mfma_f32_16x16x32_bf16 v[86:89], v[172:175], v[202:205], v[86:89]
	v_mfma_f32_16x16x32_bf16 v[86:89], v[176:179], v[206:209], v[86:89]
	v_mfma_f32_16x16x32_bf16 v[70:73], v[172:175], v[210:213], v[70:73]
	v_mfma_f32_16x16x32_bf16 v[70:73], v[176:179], v[214:217], v[70:73]
	s_setprio 0
	s_barrier
; #define PG8_STAGE(bufoff, gbase, voff) do { _Pragma("unroll") for (int _i = 0; _i < 2; ++_i) \
;         __builtin_amdgcn_global_load_lds((const unsigned*)((const char*)(gbase) + (voff)[_i]), (PG8_LAS unsigned*)(lds + (bufoff) + ldsw + _i * 8192), 16, 0, 0); } while (0)
; #define PG8_LDA(dst, b, h) do { _Pragma("unroll") for (int m = 0; m < 4; ++m) _Pragma("unroll") for (int k = 0; k < 2; ++k) dst[m][k] = *(const PG8_LAS bf16x8*)(lds + PG8_SA(b, h) + aoff + m * 2048 + k * 1024); } while (0)
; #define PG8_MMA(ai, bj, At, Bt) do { __builtin_amdgcn_s_setprio(1); _Pragma("unroll") for (int m = 0; m < 4; ++m) _Pragma("unroll") for (int n = 0; n < 2; ++n) _Pragma("unroll") for (int k = 0; k < 2; ++k) \
;         acc[ai][bj][m][n] = __builtin_amdgcn_mfma_f32_16x16x32_bf16(Bt[n][k], At[m][k], acc[ai][bj][m][n], 0, 0, 0); __builtin_amdgcn_s_setprio(0); } while (0)
; #define PG8_WAIT_V(n) asm volatile("s_waitcnt vmcnt(" #n ")" ::: "memory")
; #define PG8_WAIT_L(n) asm volatile("s_waitcnt lgkmcnt(" #n ")" ::: "memory")
; #define PG8_BAR __builtin_amdgcn_s_barrier()
; #define PG8_SCHED __builtin_amdgcn_sched_barrier(0)
; template <class Epi, class Sched, bool ALIGN_EPI = false, bool SP2 = false>
; __device__ __forceinline__ void gemm_phase(PG8_LAS unsigned char* lds, const Gemm g, const Sched& S, const Epi& E) {
;     ...
;         for (int t = 0; t < nt; t += 2) {
;     ...
;             PG8_LDA(At, 1, 1); PG8_STAGE(PG8_SB(1, 0), b3, voffB); PG8_STAGE(PG8_SB(1, 1), b3 + hstep, voffB); PG8_STAGE(PG8_SA(1, 0), a3, voffA);
;             PG8_WAIT_V(8); PG8_WAIT_L(0); PG8_BAR; PG8_MMA(1, 0, At, B0); PG8_MMA(1, 1, At, B1); PG8_BAR; PG8_SCHED;
	s_add_i32 s38, s38, s75
	v_lshl_add_u64 v[218:219], v[218:219], 0, s[30:31]
	s_mov_b32 m0, s38
	ds_read_b128 v[180:183], v170 offset:49152
	ds_read_b128 v[184:187], v170 offset:50176
	ds_read_b128 v[188:191], v170 offset:51200
	ds_read_b128 v[192:195], v170 offset:52224
	ds_read_b128 v[202:205], v170 offset:53248
	ds_read_b128 v[206:209], v170 offset:54272
	ds_read_b128 v[210:213], v170 offset:55296
	ds_read_b128 v[214:217], v170 offset:56320
	global_load_lds_dwordx4 v[218:219], off
	s_add_i32 m0, s38, 0x2000
	s_add_u32 s46, s46, 0x40080
	v_lshl_add_u64 v[218:219], v[220:221], 0, s[30:31]
	s_addc_u32 s47, s47, 0
	s_add_i32 s38, s39, s75
	global_load_lds_dwordx4 v[218:219], off
	v_lshl_add_u64 v[218:219], s[46:47], 0, v[134:135]
	s_mov_b32 m0, s38
	s_nop 0
	global_load_lds_dwordx4 v[218:219], off
	v_lshl_add_u64 v[218:219], s[46:47], 0, v[130:131]
	s_add_i32 m0, s38, 0x2000
	s_nop 0
	global_load_lds_dwordx4 v[218:219], off
	v_lshl_add_u64 v[218:219], v[222:223], 0, s[30:31]
	s_mov_b32 m0, s80
	s_nop 0
	global_load_lds_dwordx4 v[218:219], off
	v_lshl_add_u64 v[218:219], v[224:225], 0, s[30:31]
	s_mov_b32 m0, s81
	s_nop 0
	global_load_lds_dwordx4 v[218:219], off
	s_nop 0
	s_waitcnt vmcnt(8)
	s_waitcnt lgkmcnt(0)
	s_barrier
	s_setprio 1
	v_mfma_f32_16x16x32_bf16 v[58:61], v[142:145], v[180:183], v[58:61]
	v_mfma_f32_16x16x32_bf16 v[58:61], v[146:149], v[184:187], v[58:61]
	v_mfma_f32_16x16x32_bf16 v[42:45], v[142:145], v[188:191], v[42:45]
	v_mfma_f32_16x16x32_bf16 v[42:45], v[146:149], v[192:195], v[42:45]
	v_mfma_f32_16x16x32_bf16 v[26:29], v[142:145], v[202:205], v[26:29]
	v_mfma_f32_16x16x32_bf16 v[26:29], v[146:149], v[206:209], v[26:29]
	v_mfma_f32_16x16x32_bf16 v[10:13], v[142:145], v[210:213], v[10:13]
	v_mfma_f32_16x16x32_bf16 v[10:13], v[146:149], v[214:217], v[10:13]
	v_mfma_f32_16x16x32_bf16 v[62:65], v[150:153], v[180:183], v[62:65]
	v_mfma_f32_16x16x32_bf16 v[62:65], v[154:157], v[184:187], v[62:65]
	v_mfma_f32_16x16x32_bf16 v[46:49], v[150:153], v[188:191], v[46:49]
	v_mfma_f32_16x16x32_bf16 v[46:49], v[154:157], v[192:195], v[46:49]
	v_mfma_f32_16x16x32_bf16 v[30:33], v[150:153], v[202:205], v[30:33]
	v_mfma_f32_16x16x32_bf16 v[30:33], v[154:157], v[206:209], v[30:33]
	v_mfma_f32_16x16x32_bf16 v[14:17], v[150:153], v[210:213], v[14:17]
	v_mfma_f32_16x16x32_bf16 v[14:17], v[154:157], v[214:217], v[14:17]
	v_mfma_f32_16x16x32_bf16 v[50:53], v[158:161], v[180:183], v[50:53]
	v_mfma_f32_16x16x32_bf16 v[50:53], v[162:165], v[184:187], v[50:53]
	v_mfma_f32_16x16x32_bf16 v[34:37], v[158:161], v[188:191], v[34:37]
	v_mfma_f32_16x16x32_bf16 v[34:37], v[162:165], v[192:195], v[34:37]
	v_mfma_f32_16x16x32_bf16 v[18:21], v[158:161], v[202:205], v[18:21]
	v_mfma_f32_16x16x32_bf16 v[18:21], v[162:165], v[206:209], v[18:21]
	v_mfma_f32_16x16x32_bf16 v[2:5], v[158:161], v[210:213], v[2:5]
	v_mfma_f32_16x16x32_bf16 v[2:5], v[162:165], v[214:217], v[2:5]
	v_mfma_f32_16x16x32_bf16 v[54:57], v[172:175], v[180:183], v[54:57]
	v_mfma_f32_16x16x32_bf16 v[54:57], v[176:179], v[184:187], v[54:57]
	v_mfma_f32_16x16x32_bf16 v[38:41], v[172:175], v[188:191], v[38:41]
	v_mfma_f32_16x16x32_bf16 v[38:41], v[176:179], v[192:195], v[38:41]
	v_mfma_f32_16x16x32_bf16 v[22:25], v[172:175], v[202:205], v[22:25]
	v_mfma_f32_16x16x32_bf16 v[22:25], v[176:179], v[206:209], v[22:25]
	v_mfma_f32_16x16x32_bf16 v[6:9], v[172:175], v[210:213], v[6:9]
	v_mfma_f32_16x16x32_bf16 v[6:9], v[176:179], v[214:217], v[6:9]
	s_setprio 0
	s_barrier
	s_add_i32 s84, s84, 2
	s_add_u32 s48, s48, 0x100
	s_addc_u32 s49, s49, 0
	s_add_u32 s53, s53, 0x100
	s_addc_u32 s69, s69, 0
	s_cmp_gt_u32 s84, 13
	s_cbranch_scc0 .LBB0_408
	s_and_b64 vcc, exec, s[64:65]
	s_cbranch_vccz .LBB0_411
	s_barrier
